# scan: 2-chunk-deep row prefetch (second register set, parity-unrolled D/A/L) + natten: k-block loads hoisted, 8 contiguous keys per lane, dwordx4 V loads
# speedup vs baseline: 1.0065x; 1.0065x over previous
; __device__ void rwkv_scan_item(int tid_, int bid_, int nblk_, const Params& p, int li, int item, char* smem) {
;     ...
;   const float w0v = p.ev_w0[(li * 2 + dir) * DA + h * 64 + keyB];
;   const float a0v = p.ev_a0[(li * 2 + dir) * DA + h * 64 + keyB];
;   const float kav = p.ev_k_a[li * DA + h * 64 + keyB];
;   bf16x8 bw[2], ba[2];
;   {
;     const float* wu = p.ev_w_up + (size_t)(li * 2 + dir) * 64 * DA + h * 64 + keyB;
;     const float* au = p.ev_a_up + (size_t)(li * 2 + dir) * 64 * DA + h * 64 + keyB;
; #pragma unroll
;     for (int ks = 0; ks < 2; ++ks)
; #pragma unroll
;       for (int j = 0; j < 8; ++j) {
;         int k = ks * 32 + fq * 8 + j;
;         bw[ks][j] = (short)f2bf(wu[(size_t)k * DA]);
;         ba[ks][j] = (short)f2bf(au[(size_t)k * DA]);
;       }
;   }
;   const int rlC = 8 * w + (lane >> 3), ksC = lane & 7;
;   const int vrowC = half * 32 + rlC;
;   v2f S[4];
; #pragma unroll
;   for (int k = 0; k < 4; ++k) S[k] = v2f{0.f, 0.f};
;   auto load_pre = [&](int gc, Pre& pre, int sA_s, int sA_cc) {
;     int rowbase, T, tb;
;     chunk_info(gc, b, dir, rowbase, T, tb);
;     int t = dir ? (tb + 15 - sA_s) : (tb + sA_s);
;     const u16* base = P + (size_t)(rowbase + t) * EV_IN + sA_cc * 4;
; #pragma unroll
;     for (int g = 0; g < 5; ++g) {
;       pre.cur[g] = *(const uint2*)(base + goff[g]);
;       pre.prv[g] = (t > 0) ? *(const uint2*)(base - EV_IN + goff[g]) : make_uint2(0u, 0u);
;       pre.nxt[g] = (t < T - 1) ? *(const uint2*)(base + EV_IN + goff[g]) : make_uint2(0u, 0u);
;     }
;   };
;   Pre pre;
;   load_pre(0, pre, sA_s0, sA_cc0);
;   __syncthreads();
.LBB0_472:
	s_or_b64 exec, exec, s[20:21]
	s_waitcnt vmcnt(24)
	v_bfe_u32 v1, v35, 16, 1
	v_bfe_u32 v5, v29, 16, 1
	v_bfe_u32 v8, v19, 16, 1
	v_bfe_u32 v9, v15, 16, 1
	v_bfe_u32 v4, v32, 16, 1
	v_bfe_u32 v7, v22, 16, 1
	v_bfe_u32 v43, v13, 16, 1
	v_add3_u32 v9, v15, v9, s63
	v_add3_u32 v8, v19, v8, s63
	v_add3_u32 v15, v29, v5, s63
	v_add3_u32 v1, v35, v1, s63
	s_waitcnt vmcnt(23)
	v_bfe_u32 v5, v27, 16, 1
	v_bfe_u32 v19, v23, 16, 1
	v_bfe_u32 v29, v14, 16, 1
	v_bfe_u32 v35, v11, 16, 1
	s_and_b32 s24, s52, 1
	v_add3_u32 v13, v13, v43, s63
	v_add3_u32 v7, v22, v7, s63
	v_add3_u32 v4, v32, v4, s63
	s_waitcnt vmcnt(19)
	v_bfe_u32 v22, v20, 16, 1
	v_bfe_u32 v32, v12, 16, 1
	v_bfe_u32 v43, v10, 16, 1
	v_add3_u32 v11, v11, v35, s63
	v_add3_u32 v14, v14, v29, s63
	v_add3_u32 v19, v23, v19, s63
	v_add3_u32 v23, v27, v5, s63
	s_waitcnt vmcnt(8)
	v_bfe_u32 v5, v42, 16, 1
	v_bfe_u32 v29, v36, 16, 1
	v_bfe_u32 v35, v30, 16, 1
	s_movk_i32 s20, 0x80
	v_readlane_b32 s36, v254, 11
	v_add3_u32 v10, v10, v43, s63
	v_add3_u32 v12, v12, v32, s63
	v_add3_u32 v22, v20, v22, s63
	s_waitcnt vmcnt(5)
	v_bfe_u32 v20, v41, 16, 1
	v_bfe_u32 v32, v33, 16, 1
	v_bfe_u32 v43, v26, 16, 1
	v_add3_u32 v30, v30, v35, s63
	v_add3_u32 v29, v36, v29, s63
	v_add3_u32 v35, v42, v5, s63
	v_bfe_u32 v5, v39, 16, 1
	v_bfe_u32 v36, v34, 16, 1
	s_lshl_b32 s25, s29, 12
	v_cmp_gt_i32_e64 s[94:95], s20, v118
	v_lshrrev_b32_e32 v2, 1, v2
	s_lshl_b32 s20, s24, 7
	v_readlane_b32 s44, v254, 19
	v_add3_u32 v26, v26, v43, s63
	v_add3_u32 v32, v33, v32, s63
	v_add3_u32 v33, v41, v20, s63
	v_bfe_u32 v20, v37, 16, 1
	v_bfe_u32 v43, v17, 16, 1
	v_add3_u32 v34, v34, v36, s63
	v_add3_u32 v36, v39, v5, s63
	v_lshlrev_b32_e32 v5, 4, v118
	v_and_b32_e32 v2, 28, v2
	v_readlane_b32 s45, v254, 20
	s_add_u32 s21, s44, s27
	v_bfe_u32 v6, v25, 16, 1
	v_bfe_u32 v42, v21, 16, 1
	v_add3_u32 v43, v17, v43, s63
	v_add3_u32 v17, v37, v20, s63
	v_and_b32_e32 v20, 0x70, v5
	v_mul_u32_u24_e32 v5, 0x48, v119
	v_lshlrev_b32_e32 v37, 4, v3
	v_lshl_or_b32 v164, s28, 5, v2
	s_addc_u32 s22, s45, 0
	v_add3_u32 v6, v25, v6, s63
	v_bfe_u32 v25, v16, 16, 1
	v_add3_u32 v21, v21, v42, s63
	v_lshl_add_u32 v162, v5, 1, v37
	v_lshlrev_b32_e32 v37, 8, v3
	v_lshlrev_b32_e32 v3, 5, v118
	v_add_u32_e32 v165, s20, v164
	s_add_u32 s20, s21, s20
	v_add3_u32 v16, v16, v25, s63
	v_bfe_u32 v25, v40, 16, 1
	v_bfe_u32 v27, v38, 16, 1
	v_and_b32_e32 v163, 0xe0, v3
	v_perm_b32 v3, v7, v8, s88
	v_perm_b32 v7, v14, v12, s88
	v_perm_b32 v14, v21, v43, s88
	s_addc_u32 s21, s22, 0
	v_mov_b32_e32 v21, v0
	v_add3_u32 v27, v38, v27, s63
	v_add3_u32 v25, v40, v25, s63
	v_bfe_u32 v38, v31, 16, 1
	v_bfe_u32 v40, v28, 16, 1
	v_bfe_u32 v41, v24, 16, 1
	v_readlane_b32 s46, v254, 21
	v_lshl_add_u64 v[148:149], s[20:21], 0, v[20:21]
	s_lshl_b32 s20, s30, 2
	v_add3_u32 v24, v24, v41, s63
	v_add3_u32 v28, v28, v40, s63
	v_add3_u32 v31, v31, v38, s63
	v_ashrrev_i32_e32 v159, 3, v118
	v_readlane_b32 s47, v254, 22
	s_add_u32 s54, s46, s20
	v_not_b32_e32 v160, v159
	v_lshl_or_b32 v161, v159, 7, v20
	s_mul_i32 s52, s31, 0x4400
	s_mov_b32 s53, s1
	v_perm_b32 v5, v1, v4, s88
	v_perm_b32 v4, v15, v6, s88
	v_perm_b32 v2, v9, v13, s88
	v_perm_b32 v9, v23, v19, s88
	v_perm_b32 v8, v22, v16, s88
	v_perm_b32 v6, v11, v10, s88
	v_perm_b32 v13, v35, v33, s88
	v_perm_b32 v12, v25, v27, s88
	v_perm_b32 v11, v29, v32, s88
	v_perm_b32 v10, v30, v26, s88
	v_perm_b32 v17, v36, v17, s88
	v_perm_b32 v16, v34, v31, s88
	v_perm_b32 v15, v28, v24, s88
	v_add_lshl_u32 v166, v18, v37, 2
	s_addc_u32 s55, s47, 0
	s_mov_b32 s27, 0
	v_mov_b32_e32 v167, -1
	v_mov_b32_e32 v38, 0
	v_mov_b32_e32 v39, v158
	v_mov_b32_e32 v40, 0
	v_mov_b32_e32 v41, v158
	v_mov_b32_e32 v42, 0
	v_mov_b32_e32 v43, v158
	v_mov_b32_e32 v44, 0
	v_mov_b32_e32 v45, v158
	s_waitcnt lgkmcnt(0)
	s_barrier
	v_readlane_b32 s37, v254, 12
	v_readlane_b32 s38, v254, 13
	v_readlane_b32 s39, v254, 14
	v_readlane_b32 s40, v254, 15
	v_readlane_b32 s41, v254, 16
	v_readlane_b32 s42, v254, 17
	v_readlane_b32 s43, v254, 18
	v_readlane_b32 s48, v254, 23
	v_readlane_b32 s49, v254, 24
	v_readlane_b32 s50, v254, 25
	v_readlane_b32 s51, v254, 26
	s_waitcnt vmcnt(0)
	s_branch .LBB0_476

; __device__ void rwkv_scan_item(int tid_, int bid_, int nblk_, const Params& p, int li, int item, char* smem) {
;     ...
;   for (int gc = 0; gc <= NGC; ++gc) {
;     int sA_s = sA_s0, sA_cc = sA_cc0;
;     asm volatile("" : "+v"(sA_s), "+v"(sA_cc));
;     if (gc > 0) {
.LBB0_475:
	s_and_b64 vcc, exec, s[20:21]
	s_mov_b32 s27, s22
	s_cbranch_vccnz .LBB0_506
	s_bitcmp1_b32 s27, 0
	s_cbranch_scc1 .Lscanb_476

; __device__ __forceinline__ float bflo(unsigned v) { return __uint_as_float(v << 16); }
; __device__ __forceinline__ float bfhi(unsigned v) { return __uint_as_float(v & 0xffff0000u); }
; __device__ void rwkv_scan_item(int tid_, int bid_, int nblk_, const Params& p, int li, int item, char* smem) {
;     ...
;       float val[5][4];
; #pragma unroll
;       for (int g = 0; g < 5; ++g) {
;         float4 m0 = *(const float4*)(sMu0 + g * 64 + sA_cc * 4);
;         float4 m1 = *(const float4*)(sMu1 + g * 64 + sA_cc * 4);
;         float c0 = bflo(pre.cur[g].x), c1 = bfhi(pre.cur[g].x), c2 = bflo(pre.cur[g].y), c3 = bfhi(pre.cur[g].y);
;         float p0 = bflo(pre.prv[g].x), p1 = bfhi(pre.prv[g].x), p2 = bflo(pre.prv[g].y), p3 = bfhi(pre.prv[g].y);
;         float n0 = bflo(pre.nxt[g].x), n1 = bfhi(pre.nxt[g].x), n2 = bflo(pre.nxt[g].y), n3 = bfhi(pre.nxt[g].y);
;         val[g][0] = c0 + m0.x * (p0 - c0) + m1.x * (n0 - c0);
;         val[g][1] = c1 + m0.y * (p1 - c1) + m1.y * (n1 - c1);
;         val[g][2] = c2 + m0.z * (p2 - c2) + m1.z * (n2 - c2);
;         val[g][3] = c3 + m0.w * (p3 - c3) + m1.w * (n3 - c3);
;       }
;       const int so = sA_s * 64 + sA_cc * 4;
;       *(float4*)(sR + so) = make_float4(val[0][0], val[0][1], val[0][2], val[0][3]);
;       *(float4*)(sK + so) = make_float4(val[1][0], val[1][1], val[1][2], val[1][3]);
;       *(float4*)(sV + so) = make_float4(val[2][0], val[2][1], val[2][2], val[2][3]);
.LBB0_484:
	s_and_b64 vcc, exec, s[22:23]
	v_readfirstlane_b32 s22, v0
	s_cbranch_vccz .LBB0_475
	v_lshlrev_b32_e32 v49, 4, v48
	ds_read_b128 v[18:21], v49 offset:38144
	ds_read_b128 v[22:25], v49 offset:39424
	s_waitcnt vmcnt(15)
	v_lshlrev_b32_e32 v46, 16, v138
	v_lshlrev_b32_e32 v57, 16, v142
	v_lshlrev_b32_e32 v56, 16, v140
	v_pk_add_f32 v[56:57], v[56:57], v[46:47] op_sel_hi:[1,0] neg_lo:[0,1] neg_hi:[0,1]
	s_waitcnt lgkmcnt(1)
	v_mov_b32_e32 v58, v18
	s_waitcnt lgkmcnt(0)
	v_mov_b32_e32 v59, v22
	v_pk_mul_f32 v[56:57], v[56:57], v[58:59]
	v_and_b32_e32 v50, 0xffff0000, v138
	v_add_f32_e32 v18, v56, v46
	v_add_f32_e32 v51, v18, v57
	v_and_b32_e32 v47, 0xffff0000, v142
	v_and_b32_e32 v46, 0xffff0000, v140
	v_pk_add_f32 v[46:47], v[46:47], v[50:51] op_sel_hi:[1,0] neg_lo:[0,1] neg_hi:[0,1]
	v_mov_b32_e32 v22, v19
	v_pk_mul_f32 v[18:19], v[46:47], v[22:23]
	v_lshlrev_b32_e32 v52, 16, v139
	v_add_f32_e32 v18, v18, v50
	v_add_f32_e32 v55, v18, v19
	v_lshlrev_b32_e32 v19, 16, v143
	v_lshlrev_b32_e32 v18, 16, v141
	v_pk_add_f32 v[18:19], v[18:19], v[52:53] op_sel_hi:[1,0] neg_lo:[0,1] neg_hi:[0,1]
	v_mov_b32_e32 v22, v20
	v_mov_b32_e32 v23, v24
	v_pk_mul_f32 v[18:19], v[18:19], v[22:23]
	v_and_b32_e32 v54, 0xffff0000, v139
	v_add_f32_e32 v18, v18, v52
	v_add_f32_e32 v56, v18, v19
	v_and_b32_e32 v19, 0xffff0000, v143
	v_and_b32_e32 v18, 0xffff0000, v141
	v_pk_add_f32 v[18:19], v[18:19], v[54:55] op_sel_hi:[1,0] neg_lo:[0,1] neg_hi:[0,1]
	v_mov_b32_e32 v24, v21
	v_pk_mul_f32 v[18:19], v[18:19], v[24:25]
	v_lshlrev_b32_e32 v30, 16, v126
	v_add_f32_e32 v18, v18, v54
	v_add_f32_e32 v54, v18, v19
	ds_read_b128 v[18:21], v49 offset:37632
	ds_read_b128 v[22:25], v49 offset:38912
	v_and_b32_e32 v31, 0xffff0000, v126
	v_lshlrev_b32_e32 v46, 16, v128
	v_and_b32_e32 v47, 0xffff0000, v128
	v_lshlrev_b32_e32 v52, 16, v130
	v_and_b32_e32 v53, 0xffff0000, v130
	v_pk_add_f32 v[46:47], v[46:47], v[30:31] neg_lo:[0,1] neg_hi:[0,1]
	v_lshlrev_b32_e32 v32, 16, v127
	s_waitcnt lgkmcnt(1)
	v_pk_fma_f32 v[18:19], v[46:47], v[18:19], v[30:31]
	v_pk_add_f32 v[30:31], v[52:53], v[30:31] neg_lo:[0,1] neg_hi:[0,1]
	v_and_b32_e32 v33, 0xffff0000, v127
	s_waitcnt lgkmcnt(0)
	v_pk_fma_f32 v[18:19], v[30:31], v[22:23], v[18:19]
	v_lshlrev_b32_e32 v22, 16, v129
	v_and_b32_e32 v23, 0xffff0000, v129
	v_lshlrev_b32_e32 v30, 16, v131
	v_and_b32_e32 v31, 0xffff0000, v131
	v_pk_add_f32 v[22:23], v[22:23], v[32:33] neg_lo:[0,1] neg_hi:[0,1]
	v_lshlrev_b32_e32 v34, 16, v120
	v_pk_fma_f32 v[20:21], v[22:23], v[20:21], v[32:33]
	v_pk_add_f32 v[22:23], v[30:31], v[32:33] neg_lo:[0,1] neg_hi:[0,1]
	v_and_b32_e32 v35, 0xffff0000, v120
	v_pk_fma_f32 v[20:21], v[22:23], v[24:25], v[20:21]
	ds_read_b128 v[22:25], v49 offset:37376
	ds_read_b128 v[30:33], v49 offset:38656
	v_lshlrev_b32_e32 v46, 16, v122
	v_and_b32_e32 v47, 0xffff0000, v122
	v_lshlrev_b32_e32 v52, 16, v124
	v_and_b32_e32 v53, 0xffff0000, v124
	v_pk_add_f32 v[46:47], v[46:47], v[34:35] neg_lo:[0,1] neg_hi:[0,1]
	v_lshlrev_b32_e32 v36, 16, v121
	s_waitcnt lgkmcnt(1)
	v_pk_fma_f32 v[22:23], v[46:47], v[22:23], v[34:35]
	v_pk_add_f32 v[34:35], v[52:53], v[34:35] neg_lo:[0,1] neg_hi:[0,1]
	v_and_b32_e32 v37, 0xffff0000, v121
	s_waitcnt lgkmcnt(0)
	v_pk_fma_f32 v[22:23], v[34:35], v[30:31], v[22:23]
	v_lshlrev_b32_e32 v30, 16, v123
	v_and_b32_e32 v31, 0xffff0000, v123
	v_lshlrev_b32_e32 v34, 16, v125
	v_and_b32_e32 v35, 0xffff0000, v125
	v_pk_add_f32 v[30:31], v[30:31], v[36:37] neg_lo:[0,1] neg_hi:[0,1]
	v_lshlrev_b32_e32 v26, 16, v132
	v_pk_fma_f32 v[24:25], v[30:31], v[24:25], v[36:37]
	v_pk_add_f32 v[30:31], v[34:35], v[36:37] neg_lo:[0,1] neg_hi:[0,1]
	v_and_b32_e32 v27, 0xffff0000, v132
	v_pk_fma_f32 v[24:25], v[30:31], v[32:33], v[24:25]
	ds_read_b128 v[30:33], v49 offset:37888
	ds_read_b128 v[34:37], v49 offset:39168
	v_lshlrev_b32_e32 v46, 16, v134
	v_and_b32_e32 v47, 0xffff0000, v134
	v_lshlrev_b32_e32 v52, 16, v136
	v_and_b32_e32 v53, 0xffff0000, v136
	v_pk_add_f32 v[46:47], v[46:47], v[26:27] neg_lo:[0,1] neg_hi:[0,1]
	v_lshlrev_b32_e32 v28, 16, v133
	s_waitcnt lgkmcnt(1)
	v_pk_fma_f32 v[30:31], v[46:47], v[30:31], v[26:27]
	v_pk_add_f32 v[26:27], v[52:53], v[26:27] neg_lo:[0,1] neg_hi:[0,1]
	v_and_b32_e32 v29, 0xffff0000, v133
	s_waitcnt lgkmcnt(0)
	v_pk_fma_f32 v[26:27], v[26:27], v[34:35], v[30:31]
	v_lshlrev_b32_e32 v30, 16, v135
	v_and_b32_e32 v31, 0xffff0000, v135
	v_lshlrev_b32_e32 v34, 16, v137
	v_and_b32_e32 v35, 0xffff0000, v137
	v_pk_add_f32 v[30:31], v[30:31], v[28:29] neg_lo:[0,1] neg_hi:[0,1]
	s_movk_i32 s20, 0x90
	v_pk_fma_f32 v[30:31], v[30:31], v[32:33], v[28:29]
	v_pk_add_f32 v[28:29], v[34:35], v[28:29] neg_lo:[0,1] neg_hi:[0,1]
	v_add_f32_e32 v33, v54, v54
	v_pk_fma_f32 v[28:29], v[28:29], v[36:37], v[30:31]
	v_add_f32_e32 v31, v55, v55
	v_mul_f32_e32 v31, 0x3fb8aa3b, v31
	v_exp_f32_e32 v31, v31
	v_add_f32_e32 v30, v51, v51
	v_mul_f32_e32 v30, 0x3fb8aa3b, v30
	v_exp_f32_e32 v30, v30
	v_add_f32_e32 v31, 1.0, v31
	v_rcp_f32_e32 v32, v31
	v_add_f32_e32 v31, v56, v56
	v_mul_f32_e32 v31, 0x3fb8aa3b, v31
	v_exp_f32_e32 v31, v31
	v_mul_f32_e32 v33, 0x3fb8aa3b, v33
	v_exp_f32_e32 v33, v33
	v_add_f32_e32 v30, 1.0, v30
	v_add_f32_e32 v31, 1.0, v31
	v_rcp_f32_e32 v30, v30
	v_rcp_f32_e32 v31, v31
	v_add_f32_e32 v33, 1.0, v33
	v_rcp_f32_e32 v33, v33
	v_mul_lo_u32 v34, v1, s20
	v_pk_fma_f32 v[30:31], v[30:31], 2.0, 1.0 op_sel_hi:[1,0,0] neg_lo:[1,0,0] neg_hi:[1,0,0]
	v_lshl_add_u32 v51, v48, 3, v34
	v_pk_fma_f32 v[32:33], v[32:33], 2.0, 1.0 op_sel_hi:[1,0,0] neg_lo:[1,0,0] neg_hi:[1,0,0]
	v_and_b32_sdwa v34, v31, v198 dst_sel:DWORD dst_unused:UNUSED_PAD src0_sel:WORD_1 src1_sel:DWORD
	v_and_b32_sdwa v35, v30, v198 dst_sel:DWORD dst_unused:UNUSED_PAD src0_sel:WORD_1 src1_sel:DWORD
	v_add3_u32 v30, v30, v35, s63
	v_add3_u32 v31, v31, v34, s63
	v_and_b32_sdwa v34, v33, v198 dst_sel:DWORD dst_unused:UNUSED_PAD src0_sel:WORD_1 src1_sel:DWORD
	v_and_b32_sdwa v35, v32, v198 dst_sel:DWORD dst_unused:UNUSED_PAD src0_sel:WORD_1 src1_sel:DWORD
	v_add3_u32 v33, v33, v34, s63
	v_add3_u32 v32, v32, v35, s63
	v_lshl_add_u32 v50, v1, 8, v49
	v_and_b32_e32 v33, 0xffff0000, v33
	v_and_b32_e32 v32, 0xffff0000, v32
	v_or_b32_sdwa v47, v33, v31 dst_sel:DWORD dst_unused:UNUSED_PAD src0_sel:DWORD src1_sel:WORD_1
	v_or_b32_sdwa v46, v32, v30 dst_sel:DWORD dst_unused:UNUSED_PAD src0_sel:DWORD src1_sel:WORD_1
	ds_read_b128 v[30:33], v49 offset:38400
	ds_read_b128 v[34:37], v49 offset:39680
	ds_write_b128 v50, v[22:25] offset:16384
	ds_write_b128 v50, v[18:21] offset:24576
	ds_write_b128 v50, v[26:29] offset:20480
	ds_read_b128 v[22:25], v49 offset:39936
	s_waitcnt vmcnt(15)
; __device__ __forceinline__ unsigned pack2(float a, float b) { return (unsigned)f2bf(a) | ((unsigned)f2bf(b) << 16); }
; __device__ __forceinline__ float tanhf_(float x) { return 1.f - 2.f * __builtin_amdgcn_rcpf(1.f + __expf(2.f * x)); }
; __device__ void rwkv_scan_item(int tid_, int bid_, int nblk_, const Params& p, int li, int item, char* smem) {
;     ...
;   auto load_pre = [&](int gc, Pre& pre, int sA_s, int sA_cc) {
;     int rowbase, T, tb;
;     chunk_info(gc, b, dir, rowbase, T, tb);
;     int t = dir ? (tb + 15 - sA_s) : (tb + sA_s);
;     const u16* base = P + (size_t)(rowbase + t) * EV_IN + sA_cc * 4;
; #pragma unroll
;     for (int g = 0; g < 5; ++g) {
;       pre.cur[g] = *(const uint2*)(base + goff[g]);
;       pre.prv[g] = (t > 0) ? *(const uint2*)(base - EV_IN + goff[g]) : make_uint2(0u, 0u);
;       pre.nxt[g] = (t < T - 1) ? *(const uint2*)(base + EV_IN + goff[g]) : make_uint2(0u, 0u);
;     }
;   };
;     ...
;       float4 kk4 = *(const float4*)(sKk + sA_cc * 4);
;       float q0 = val[1][0] * kk4.x, q1 = val[1][1] * kk4.y, q2 = val[1][2] * kk4.z, q3 = val[1][3] * kk4.w;
;       float ss = red16(q0 * q0 + q1 * q1 + q2 * q2 + q3 * q3);
;       float rn = rsqrtf(ss + 1e-12f);
;       *(float4*)(sKK + so) = make_float4(q0 * rn, q1 * rn, q2 * rn, q3 * rn);
;       uint2 tw, ta;
;       tw.x = pack2(tanhf_(val[3][0]), tanhf_(val[3][1]));
;       tw.y = pack2(tanhf_(val[3][2]), tanhf_(val[3][3]));
;       ta.x = pack2(val[4][0], val[4][1]);
;       ta.y = pack2(val[4][2], val[4][3]);
;       *(uint2*)(sAw + sA_s * 72 + sA_cc * 4) = tw;
;       *(uint2*)(sAa + sA_s * 72 + sA_cc * 4) = ta;
;     }
;     lds_barrier();
;     if (gc + 1 < NGC) load_pre(gc + 1, pre, sA_s, sA_cc);
	v_lshlrev_b32_e32 v53, 16, v145
	v_lshlrev_b32_e32 v52, 16, v144
	v_lshlrev_b32_e32 v57, 16, v147
	v_lshlrev_b32_e32 v56, 16, v146
	s_waitcnt lgkmcnt(0)
	v_pk_mul_f32 v[18:19], v[18:19], v[22:23]
	v_pk_mul_f32 v[20:21], v[20:21], v[24:25]
	v_pk_mul_f32 v[22:23], v[18:19], v[18:19]
	v_pk_mul_f32 v[24:25], v[20:21], v[20:21]
	v_add_f32_e32 v22, v22, v23
	v_add_f32_e32 v22, v22, v24
	v_add_f32_e32 v22, v22, v25
	v_lshlrev_b32_e32 v61, 16, v151
	v_lshlrev_b32_e32 v60, 16, v150
	v_add_f32_dpp v22, v22, v22 quad_perm:[1,0,3,2] row_mask:0xf bank_mask:0xf bound_ctrl:1
	v_pk_add_f32 v[56:57], v[56:57], v[52:53] neg_lo:[0,1] neg_hi:[0,1]
	v_mov_b32_e32 v64, v30
	v_add_f32_dpp v22, v22, v22 quad_perm:[2,3,0,1] row_mask:0xf bank_mask:0xf bound_ctrl:1
	v_mov_b32_e32 v65, v32
	v_and_b32_e32 v55, 0xffff0000, v145
	v_add_f32_dpp v22, v22, v22 row_half_mirror row_mask:0xf bank_mask:0xf bound_ctrl:1
	v_and_b32_e32 v54, 0xffff0000, v144
	v_and_b32_e32 v59, 0xffff0000, v147
	v_add_f32_dpp v22, v22, v22 row_mirror row_mask:0xf bank_mask:0xf bound_ctrl:1
	v_add_f32_e32 v22, 0x2b8cbccc, v22
	v_cmp_gt_f32_e32 vcc, s62, v22
	v_mul_f32_e32 v23, 0x4b800000, v22
	v_and_b32_e32 v58, 0xffff0000, v146
	v_cndmask_b32_e32 v22, v22, v23, vcc
	v_rsq_f32_e32 v22, v22
	v_pk_fma_f32 v[56:57], v[56:57], v[64:65], v[52:53]
	v_pk_add_f32 v[52:53], v[60:61], v[52:53] neg_lo:[0,1] neg_hi:[0,1]
	v_mov_b32_e32 v60, v34
	v_mov_b32_e32 v61, v36
	v_mul_f32_e32 v23, 0x45800000, v22
	v_and_b32_e32 v63, 0xffff0000, v151
	v_and_b32_e32 v62, 0xffff0000, v150
	v_pk_fma_f32 v[52:53], v[52:53], v[60:61], v[56:57]
	v_pk_add_f32 v[56:57], v[58:59], v[54:55] neg_lo:[0,1] neg_hi:[0,1]
	v_mov_b32_e32 v32, v31
	v_cndmask_b32_e32 v22, v22, v23, vcc
	v_pk_fma_f32 v[30:31], v[56:57], v[32:33], v[54:55]
	v_pk_add_f32 v[32:33], v[62:63], v[54:55] neg_lo:[0,1] neg_hi:[0,1]
	v_mov_b32_e32 v36, v35
	v_pk_mul_f32 v[18:19], v[18:19], v[22:23] op_sel_hi:[1,0]
	v_pk_mul_f32 v[20:21], v[20:21], v[22:23] op_sel_hi:[1,0]
	v_pk_fma_f32 v[30:31], v[32:33], v[36:37], v[30:31]
	ds_write_b128 v50, v[18:21] offset:4096
	v_and_b32_sdwa v19, v52, v198 dst_sel:DWORD dst_unused:UNUSED_PAD src0_sel:WORD_1 src1_sel:DWORD
	v_add3_u32 v20, v52, v19, s63
	v_and_b32_sdwa v19, v31, v198 dst_sel:DWORD dst_unused:UNUSED_PAD src0_sel:WORD_1 src1_sel:DWORD
	v_and_b32_sdwa v21, v30, v198 dst_sel:DWORD dst_unused:UNUSED_PAD src0_sel:WORD_1 src1_sel:DWORD
	v_and_b32_sdwa v18, v53, v198 dst_sel:DWORD dst_unused:UNUSED_PAD src0_sel:WORD_1 src1_sel:DWORD
	v_add3_u32 v19, v31, v19, s63
	v_add3_u32 v21, v30, v21, s63
	v_add3_u32 v18, v53, v18, s63
	v_and_b32_e32 v19, 0xffff0000, v19
	v_and_b32_e32 v21, 0xffff0000, v21
	v_or_b32_sdwa v19, v19, v18 dst_sel:DWORD dst_unused:UNUSED_PAD src0_sel:DWORD src1_sel:WORD_1
	v_or_b32_sdwa v18, v21, v20 dst_sel:DWORD dst_unused:UNUSED_PAD src0_sel:DWORD src1_sel:WORD_1
	ds_write_b64 v51, v[46:47] offset:32768
	ds_write_b64 v51, v[18:19] offset:35072
	s_waitcnt lgkmcnt(0)
	s_barrier
	s_cmp_lg_u32 s27, 0
	s_cbranch_scc1 .Lscan_noLp
	s_cmp_lt_u32 s27, 15
	s_movk_i32 s21, 0x1000
	s_cselect_b32 s22, 0x100, s21
	s_cselect_b32 s21, 16, 0xffffff10
	v_sub_u32_e32 v20, s22, v1
	v_subrev_u32_e32 v20, s21, v20
	v_add_u32_e32 v21, s21, v158
	v_add_u32_e32 v20, v167, v20
	v_add_u32_e32 v1, v21, v1
	s_cselect_b32 s20, s26, s25
	v_cndmask_b32_e64 v1, v20, v1, s[56:57]
	v_lshlrev_b32_e32 v18, 2, v48
	v_add_u32_e32 v22, s20, v1
	v_mov_b64_e32 v[20:21], s[18:19]
	v_ashrrev_i32_e32 v19, 31, v18
	v_mad_i64_i32 v[20:21], s[20:21], v22, s33, v[20:21]
	v_lshl_add_u64 v[20:21], v[18:19], 1, v[20:21]
	s_mov_b32 s59, s1
	s_mov_b32 s35, s1
	s_mov_b32 s61, s1
	s_mov_b32 s87, s1
	v_lshl_add_u64 v[18:19], v[20:21], 0, s[58:59]
	global_load_dwordx2 v[180:181], v[18:19], off
	v_lshl_add_u64 v[18:19], v[20:21], 0, s[0:1]
	global_load_dwordx2 v[186:187], v[18:19], off
	v_lshl_add_u64 v[18:19], v[20:21], 0, s[34:35]
	global_load_dwordx2 v[210:211], v[18:19], off
	v_lshl_add_u64 v[18:19], v[20:21], 0, s[60:61]
	global_load_dwordx2 v[216:217], v[18:19], off
	v_lshl_add_u64 v[18:19], v[20:21], 0, s[86:87]
	global_load_dwordx2 v[234:235], v[18:19], off
	v_mov_b32_e32 v182, v0
	v_mov_b32_e32 v183, v0
	v_mov_b32_e32 v184, v0
	v_mov_b32_e32 v185, v0
	v_mov_b32_e32 v188, v0
	v_mov_b32_e32 v189, v0
	v_mov_b32_e32 v190, v0
	v_mov_b32_e32 v191, v0
	v_mov_b32_e32 v212, v0
	v_mov_b32_e32 v213, v0
	v_mov_b32_e32 v214, v0
	v_mov_b32_e32 v215, v0
	v_mov_b32_e32 v218, v0
	v_mov_b32_e32 v219, v0
	v_mov_b32_e32 v220, v0
	v_mov_b32_e32 v221, v0
	v_mov_b32_e32 v236, v0
	v_mov_b32_e32 v237, v0
	v_mov_b32_e32 v238, v0
	v_mov_b32_e32 v239, v0
	v_cmp_lt_i32_e32 vcc, 0, v1
	s_add_i32 s22, s22, -1
	v_cmp_gt_i32_e64 s[42:43], s22, v1
	s_movk_i32 s20, 0xbe00
	s_mov_b32 s21, -1
	v_lshl_add_u64 v[22:23], v[20:21], 0, s[20:21]
	s_mov_b64 s[20:21], 0x4200
	v_lshl_add_u64 v[24:25], v[20:21], 0, s[20:21]
	s_mov_b64 s[20:21], exec
	s_and_b64 exec, s[20:21], vcc
	v_lshl_add_u64 v[18:19], v[22:23], 0, s[58:59]
	global_load_dwordx2 v[182:183], v[18:19], off
	v_lshl_add_u64 v[18:19], v[22:23], 0, s[0:1]
	global_load_dwordx2 v[188:189], v[18:19], off
	v_lshl_add_u64 v[18:19], v[22:23], 0, s[34:35]
	global_load_dwordx2 v[212:213], v[18:19], off
	v_lshl_add_u64 v[18:19], v[22:23], 0, s[60:61]
	global_load_dwordx2 v[218:219], v[18:19], off
	v_lshl_add_u64 v[18:19], v[22:23], 0, s[86:87]
	global_load_dwordx2 v[236:237], v[18:19], off
	s_and_b64 exec, s[20:21], s[42:43]
	v_lshl_add_u64 v[18:19], v[24:25], 0, s[58:59]
	global_load_dwordx2 v[184:185], v[18:19], off
	v_lshl_add_u64 v[18:19], v[24:25], 0, s[0:1]
	global_load_dwordx2 v[190:191], v[18:19], off
	v_lshl_add_u64 v[18:19], v[24:25], 0, s[34:35]
	global_load_dwordx2 v[214:215], v[18:19], off
	v_lshl_add_u64 v[18:19], v[24:25], 0, s[60:61]
	global_load_dwordx2 v[220:221], v[18:19], off
	v_lshl_add_u64 v[18:19], v[24:25], 0, s[86:87]
	global_load_dwordx2 v[238:239], v[18:19], off
	s_mov_b64 exec, s[20:21]
	v_mov_b32_e32 v1, v154
; __device__ void rwkv_scan_item(int tid_, int bid_, int nblk_, const Params& p, int li, int item, char* smem) {
;     ...
;   auto load_pre = [&](int gc, Pre& pre, int sA_s, int sA_cc) {
;     int rowbase, T, tb;
;     chunk_info(gc, b, dir, rowbase, T, tb);
;     int t = dir ? (tb + 15 - sA_s) : (tb + sA_s);
;     const u16* base = P + (size_t)(rowbase + t) * EV_IN + sA_cc * 4;
; #pragma unroll
;     for (int g = 0; g < 5; ++g) {
;       pre.cur[g] = *(const uint2*)(base + goff[g]);
;       pre.prv[g] = (t > 0) ? *(const uint2*)(base - EV_IN + goff[g]) : make_uint2(0u, 0u);
;       pre.nxt[g] = (t < T - 1) ? *(const uint2*)(base + EV_IN + goff[g]) : make_uint2(0u, 0u);
;     }
;   };
.Lscan_noLp:
	s_cmp_lt_u32 s27, 14
	s_movk_i32 s21, 0x1000
	s_cselect_b32 s22, 0x100, s21
	s_cselect_b32 s21, 32, 0xffffff20
	v_sub_u32_e32 v20, s22, v1
	v_subrev_u32_e32 v20, s21, v20
	v_add_u32_e32 v21, s21, v158
	v_add_u32_e32 v20, v167, v20
	v_add_u32_e32 v1, v21, v1
	s_cselect_b32 s20, s26, s25
	v_cndmask_b32_e64 v1, v20, v1, s[56:57]
	v_lshlrev_b32_e32 v18, 2, v48
	v_add_u32_e32 v22, s20, v1
	v_mov_b64_e32 v[20:21], s[18:19]
	v_ashrrev_i32_e32 v19, 31, v18
	v_mad_i64_i32 v[20:21], s[20:21], v22, s33, v[20:21]
	v_lshl_add_u64 v[20:21], v[18:19], 1, v[20:21]
	s_mov_b32 s59, s1
	s_mov_b32 s35, s1
	s_mov_b32 s61, s1
	s_mov_b32 s87, s1
	v_lshl_add_u64 v[18:19], v[20:21], 0, s[58:59]
	global_load_dwordx2 v[120:121], v[18:19], off
	v_lshl_add_u64 v[18:19], v[20:21], 0, s[0:1]
	global_load_dwordx2 v[126:127], v[18:19], off
	v_lshl_add_u64 v[18:19], v[20:21], 0, s[34:35]
	global_load_dwordx2 v[132:133], v[18:19], off
	v_lshl_add_u64 v[18:19], v[20:21], 0, s[60:61]
	global_load_dwordx2 v[138:139], v[18:19], off
	v_lshl_add_u64 v[18:19], v[20:21], 0, s[86:87]
	global_load_dwordx2 v[144:145], v[18:19], off
	v_mov_b32_e32 v122, v0
	v_mov_b32_e32 v123, v0
	v_mov_b32_e32 v124, v0
	v_mov_b32_e32 v125, v0
	v_mov_b32_e32 v128, v0
	v_mov_b32_e32 v129, v0
	v_mov_b32_e32 v130, v0
	v_mov_b32_e32 v131, v0
	v_mov_b32_e32 v134, v0
	v_mov_b32_e32 v135, v0
	v_mov_b32_e32 v136, v0
	v_mov_b32_e32 v137, v0
	v_mov_b32_e32 v140, v0
	v_mov_b32_e32 v141, v0
	v_mov_b32_e32 v142, v0
	v_mov_b32_e32 v143, v0
	v_mov_b32_e32 v146, v0
	v_mov_b32_e32 v147, v0
	v_mov_b32_e32 v150, v0
	v_mov_b32_e32 v151, v0
	v_cmp_lt_i32_e32 vcc, 0, v1
	s_add_i32 s22, s22, -1
	v_cmp_gt_i32_e64 s[42:43], s22, v1
	s_movk_i32 s20, 0xbe00
	s_mov_b32 s21, -1
	v_lshl_add_u64 v[22:23], v[20:21], 0, s[20:21]
	s_mov_b64 s[20:21], 0x4200
	v_lshl_add_u64 v[24:25], v[20:21], 0, s[20:21]
	s_mov_b64 s[20:21], exec
	s_and_b64 exec, s[20:21], vcc
	v_lshl_add_u64 v[18:19], v[22:23], 0, s[58:59]
	global_load_dwordx2 v[122:123], v[18:19], off
	v_lshl_add_u64 v[18:19], v[22:23], 0, s[0:1]
	global_load_dwordx2 v[128:129], v[18:19], off
	v_lshl_add_u64 v[18:19], v[22:23], 0, s[34:35]
	global_load_dwordx2 v[134:135], v[18:19], off
	v_lshl_add_u64 v[18:19], v[22:23], 0, s[60:61]
	global_load_dwordx2 v[140:141], v[18:19], off
	v_lshl_add_u64 v[18:19], v[22:23], 0, s[86:87]
	global_load_dwordx2 v[146:147], v[18:19], off
	s_and_b64 exec, s[20:21], s[42:43]
	v_lshl_add_u64 v[18:19], v[24:25], 0, s[58:59]
	global_load_dwordx2 v[124:125], v[18:19], off
	v_lshl_add_u64 v[18:19], v[24:25], 0, s[0:1]
	global_load_dwordx2 v[130:131], v[18:19], off
	v_lshl_add_u64 v[18:19], v[24:25], 0, s[34:35]
	global_load_dwordx2 v[136:137], v[18:19], off
	v_lshl_add_u64 v[18:19], v[24:25], 0, s[60:61]
	global_load_dwordx2 v[142:143], v[18:19], off
	v_lshl_add_u64 v[18:19], v[24:25], 0, s[86:87]
	global_load_dwordx2 v[150:151], v[18:19], off
	s_mov_b64 exec, s[20:21]
	s_branch .LBB0_474

; __device__ __forceinline__ float bflo(unsigned v) { return __uint_as_float(v << 16); }
; __device__ __forceinline__ float bfhi(unsigned v) { return __uint_as_float(v & 0xffff0000u); }
; __device__ void rwkv_scan_item(int tid_, int bid_, int nblk_, const Params& p, int li, int item, char* smem) {
;     ...
;       float val[5][4];
; #pragma unroll
;       for (int g = 0; g < 5; ++g) {
;         float4 m0 = *(const float4*)(sMu0 + g * 64 + sA_cc * 4);
;         float4 m1 = *(const float4*)(sMu1 + g * 64 + sA_cc * 4);
;         float c0 = bflo(pre.cur[g].x), c1 = bfhi(pre.cur[g].x), c2 = bflo(pre.cur[g].y), c3 = bfhi(pre.cur[g].y);
;         float p0 = bflo(pre.prv[g].x), p1 = bfhi(pre.prv[g].x), p2 = bflo(pre.prv[g].y), p3 = bfhi(pre.prv[g].y);
;         float n0 = bflo(pre.nxt[g].x), n1 = bfhi(pre.nxt[g].x), n2 = bflo(pre.nxt[g].y), n3 = bfhi(pre.nxt[g].y);
;         val[g][0] = c0 + m0.x * (p0 - c0) + m1.x * (n0 - c0);
;         val[g][1] = c1 + m0.y * (p1 - c1) + m1.y * (n1 - c1);
;         val[g][2] = c2 + m0.z * (p2 - c2) + m1.z * (n2 - c2);
;         val[g][3] = c3 + m0.w * (p3 - c3) + m1.w * (n3 - c3);
;       }
;       const int so = sA_s * 64 + sA_cc * 4;
;       *(float4*)(sR + so) = make_float4(val[0][0], val[0][1], val[0][2], val[0][3]);
;       *(float4*)(sK + so) = make_float4(val[1][0], val[1][1], val[1][2], val[1][3]);
;       *(float4*)(sV + so) = make_float4(val[2][0], val[2][1], val[2][2], val[2][3]);
.Lscanb_484:
	s_and_b64 vcc, exec, s[22:23]
	v_readfirstlane_b32 s22, v0
	s_cbranch_vccz .LBB0_475
	v_lshlrev_b32_e32 v49, 4, v48
	ds_read_b128 v[18:21], v49 offset:38144
	ds_read_b128 v[22:25], v49 offset:39424
	s_waitcnt vmcnt(15)
	v_lshlrev_b32_e32 v46, 16, v216
	v_lshlrev_b32_e32 v57, 16, v220
	v_lshlrev_b32_e32 v56, 16, v218
	v_pk_add_f32 v[56:57], v[56:57], v[46:47] op_sel_hi:[1,0] neg_lo:[0,1] neg_hi:[0,1]
	s_waitcnt lgkmcnt(1)
	v_mov_b32_e32 v58, v18
	s_waitcnt lgkmcnt(0)
	v_mov_b32_e32 v59, v22
	v_pk_mul_f32 v[56:57], v[56:57], v[58:59]
	v_and_b32_e32 v50, 0xffff0000, v216
	v_add_f32_e32 v18, v56, v46
	v_add_f32_e32 v51, v18, v57
	v_and_b32_e32 v47, 0xffff0000, v220
	v_and_b32_e32 v46, 0xffff0000, v218
	v_pk_add_f32 v[46:47], v[46:47], v[50:51] op_sel_hi:[1,0] neg_lo:[0,1] neg_hi:[0,1]
	v_mov_b32_e32 v22, v19
	v_pk_mul_f32 v[18:19], v[46:47], v[22:23]
	v_lshlrev_b32_e32 v52, 16, v217
	v_add_f32_e32 v18, v18, v50
	v_add_f32_e32 v55, v18, v19
	v_lshlrev_b32_e32 v19, 16, v221
	v_lshlrev_b32_e32 v18, 16, v219
	v_pk_add_f32 v[18:19], v[18:19], v[52:53] op_sel_hi:[1,0] neg_lo:[0,1] neg_hi:[0,1]
	v_mov_b32_e32 v22, v20
	v_mov_b32_e32 v23, v24
	v_pk_mul_f32 v[18:19], v[18:19], v[22:23]
	v_and_b32_e32 v54, 0xffff0000, v217
	v_add_f32_e32 v18, v18, v52
	v_add_f32_e32 v56, v18, v19
	v_and_b32_e32 v19, 0xffff0000, v221
	v_and_b32_e32 v18, 0xffff0000, v219
	v_pk_add_f32 v[18:19], v[18:19], v[54:55] op_sel_hi:[1,0] neg_lo:[0,1] neg_hi:[0,1]
	v_mov_b32_e32 v24, v21
	v_pk_mul_f32 v[18:19], v[18:19], v[24:25]
	v_lshlrev_b32_e32 v30, 16, v186
	v_add_f32_e32 v18, v18, v54
	v_add_f32_e32 v54, v18, v19
	ds_read_b128 v[18:21], v49 offset:37632
	ds_read_b128 v[22:25], v49 offset:38912
	v_and_b32_e32 v31, 0xffff0000, v186
	v_lshlrev_b32_e32 v46, 16, v188
	v_and_b32_e32 v47, 0xffff0000, v188
	v_lshlrev_b32_e32 v52, 16, v190
	v_and_b32_e32 v53, 0xffff0000, v190
	v_pk_add_f32 v[46:47], v[46:47], v[30:31] neg_lo:[0,1] neg_hi:[0,1]
	v_lshlrev_b32_e32 v32, 16, v187
	s_waitcnt lgkmcnt(1)
	v_pk_fma_f32 v[18:19], v[46:47], v[18:19], v[30:31]
	v_pk_add_f32 v[30:31], v[52:53], v[30:31] neg_lo:[0,1] neg_hi:[0,1]
	v_and_b32_e32 v33, 0xffff0000, v187
	s_waitcnt lgkmcnt(0)
	v_pk_fma_f32 v[18:19], v[30:31], v[22:23], v[18:19]
	v_lshlrev_b32_e32 v22, 16, v189
	v_and_b32_e32 v23, 0xffff0000, v189
	v_lshlrev_b32_e32 v30, 16, v191
	v_and_b32_e32 v31, 0xffff0000, v191
	v_pk_add_f32 v[22:23], v[22:23], v[32:33] neg_lo:[0,1] neg_hi:[0,1]
	v_lshlrev_b32_e32 v34, 16, v180
	v_pk_fma_f32 v[20:21], v[22:23], v[20:21], v[32:33]
	v_pk_add_f32 v[22:23], v[30:31], v[32:33] neg_lo:[0,1] neg_hi:[0,1]
	v_and_b32_e32 v35, 0xffff0000, v180
	v_pk_fma_f32 v[20:21], v[22:23], v[24:25], v[20:21]
	ds_read_b128 v[22:25], v49 offset:37376
	ds_read_b128 v[30:33], v49 offset:38656
	v_lshlrev_b32_e32 v46, 16, v182
	v_and_b32_e32 v47, 0xffff0000, v182
	v_lshlrev_b32_e32 v52, 16, v184
	v_and_b32_e32 v53, 0xffff0000, v184
	v_pk_add_f32 v[46:47], v[46:47], v[34:35] neg_lo:[0,1] neg_hi:[0,1]
	v_lshlrev_b32_e32 v36, 16, v181
	s_waitcnt lgkmcnt(1)
	v_pk_fma_f32 v[22:23], v[46:47], v[22:23], v[34:35]
	v_pk_add_f32 v[34:35], v[52:53], v[34:35] neg_lo:[0,1] neg_hi:[0,1]
	v_and_b32_e32 v37, 0xffff0000, v181
	s_waitcnt lgkmcnt(0)
	v_pk_fma_f32 v[22:23], v[34:35], v[30:31], v[22:23]
	v_lshlrev_b32_e32 v30, 16, v183
	v_and_b32_e32 v31, 0xffff0000, v183
	v_lshlrev_b32_e32 v34, 16, v185
	v_and_b32_e32 v35, 0xffff0000, v185
	v_pk_add_f32 v[30:31], v[30:31], v[36:37] neg_lo:[0,1] neg_hi:[0,1]
	v_lshlrev_b32_e32 v26, 16, v210
	v_pk_fma_f32 v[24:25], v[30:31], v[24:25], v[36:37]
	v_pk_add_f32 v[30:31], v[34:35], v[36:37] neg_lo:[0,1] neg_hi:[0,1]
	v_and_b32_e32 v27, 0xffff0000, v210
	v_pk_fma_f32 v[24:25], v[30:31], v[32:33], v[24:25]
	ds_read_b128 v[30:33], v49 offset:37888
	ds_read_b128 v[34:37], v49 offset:39168
	v_lshlrev_b32_e32 v46, 16, v212
	v_and_b32_e32 v47, 0xffff0000, v212
	v_lshlrev_b32_e32 v52, 16, v214
	v_and_b32_e32 v53, 0xffff0000, v214
	v_pk_add_f32 v[46:47], v[46:47], v[26:27] neg_lo:[0,1] neg_hi:[0,1]
	v_lshlrev_b32_e32 v28, 16, v211
	s_waitcnt lgkmcnt(1)
	v_pk_fma_f32 v[30:31], v[46:47], v[30:31], v[26:27]
	v_pk_add_f32 v[26:27], v[52:53], v[26:27] neg_lo:[0,1] neg_hi:[0,1]
	v_and_b32_e32 v29, 0xffff0000, v211
	s_waitcnt lgkmcnt(0)
	v_pk_fma_f32 v[26:27], v[26:27], v[34:35], v[30:31]
	v_lshlrev_b32_e32 v30, 16, v213
	v_and_b32_e32 v31, 0xffff0000, v213
	v_lshlrev_b32_e32 v34, 16, v215
	v_and_b32_e32 v35, 0xffff0000, v215
	v_pk_add_f32 v[30:31], v[30:31], v[28:29] neg_lo:[0,1] neg_hi:[0,1]
	s_movk_i32 s20, 0x90
	v_pk_fma_f32 v[30:31], v[30:31], v[32:33], v[28:29]
	v_pk_add_f32 v[28:29], v[34:35], v[28:29] neg_lo:[0,1] neg_hi:[0,1]
	v_add_f32_e32 v33, v54, v54
	v_pk_fma_f32 v[28:29], v[28:29], v[36:37], v[30:31]
	v_add_f32_e32 v31, v55, v55
	v_mul_f32_e32 v31, 0x3fb8aa3b, v31
	v_exp_f32_e32 v31, v31
	v_add_f32_e32 v30, v51, v51
	v_mul_f32_e32 v30, 0x3fb8aa3b, v30
	v_exp_f32_e32 v30, v30
	v_add_f32_e32 v31, 1.0, v31
	v_rcp_f32_e32 v32, v31
	v_add_f32_e32 v31, v56, v56
	v_mul_f32_e32 v31, 0x3fb8aa3b, v31
	v_exp_f32_e32 v31, v31
	v_mul_f32_e32 v33, 0x3fb8aa3b, v33
	v_exp_f32_e32 v33, v33
	v_add_f32_e32 v30, 1.0, v30
	v_add_f32_e32 v31, 1.0, v31
	v_rcp_f32_e32 v30, v30
	v_rcp_f32_e32 v31, v31
	v_add_f32_e32 v33, 1.0, v33
	v_rcp_f32_e32 v33, v33
	v_mul_lo_u32 v34, v1, s20
	v_pk_fma_f32 v[30:31], v[30:31], 2.0, 1.0 op_sel_hi:[1,0,0] neg_lo:[1,0,0] neg_hi:[1,0,0]
	v_lshl_add_u32 v51, v48, 3, v34
	v_pk_fma_f32 v[32:33], v[32:33], 2.0, 1.0 op_sel_hi:[1,0,0] neg_lo:[1,0,0] neg_hi:[1,0,0]
	v_and_b32_sdwa v34, v31, v198 dst_sel:DWORD dst_unused:UNUSED_PAD src0_sel:WORD_1 src1_sel:DWORD
	v_and_b32_sdwa v35, v30, v198 dst_sel:DWORD dst_unused:UNUSED_PAD src0_sel:WORD_1 src1_sel:DWORD
	v_add3_u32 v30, v30, v35, s63
	v_add3_u32 v31, v31, v34, s63
	v_and_b32_sdwa v34, v33, v198 dst_sel:DWORD dst_unused:UNUSED_PAD src0_sel:WORD_1 src1_sel:DWORD
	v_and_b32_sdwa v35, v32, v198 dst_sel:DWORD dst_unused:UNUSED_PAD src0_sel:WORD_1 src1_sel:DWORD
	v_add3_u32 v33, v33, v34, s63
	v_add3_u32 v32, v32, v35, s63
	v_lshl_add_u32 v50, v1, 8, v49
	v_and_b32_e32 v33, 0xffff0000, v33
	v_and_b32_e32 v32, 0xffff0000, v32
	v_or_b32_sdwa v47, v33, v31 dst_sel:DWORD dst_unused:UNUSED_PAD src0_sel:DWORD src1_sel:WORD_1
	v_or_b32_sdwa v46, v32, v30 dst_sel:DWORD dst_unused:UNUSED_PAD src0_sel:DWORD src1_sel:WORD_1
	ds_read_b128 v[30:33], v49 offset:38400
	ds_read_b128 v[34:37], v49 offset:39680
	ds_write_b128 v50, v[22:25] offset:16384
	ds_write_b128 v50, v[18:21] offset:24576
	ds_write_b128 v50, v[26:29] offset:20480
	ds_read_b128 v[22:25], v49 offset:39936
	s_waitcnt vmcnt(15)
; __device__ __forceinline__ unsigned pack2(float a, float b) { return (unsigned)f2bf(a) | ((unsigned)f2bf(b) << 16); }
; __device__ __forceinline__ float tanhf_(float x) { return 1.f - 2.f * __builtin_amdgcn_rcpf(1.f + __expf(2.f * x)); }
; __device__ void rwkv_scan_item(int tid_, int bid_, int nblk_, const Params& p, int li, int item, char* smem) {
;     ...
;   auto load_pre = [&](int gc, Pre& pre, int sA_s, int sA_cc) {
;     int rowbase, T, tb;
;     chunk_info(gc, b, dir, rowbase, T, tb);
;     int t = dir ? (tb + 15 - sA_s) : (tb + sA_s);
;     const u16* base = P + (size_t)(rowbase + t) * EV_IN + sA_cc * 4;
; #pragma unroll
;     for (int g = 0; g < 5; ++g) {
;       pre.cur[g] = *(const uint2*)(base + goff[g]);
;       pre.prv[g] = (t > 0) ? *(const uint2*)(base - EV_IN + goff[g]) : make_uint2(0u, 0u);
;       pre.nxt[g] = (t < T - 1) ? *(const uint2*)(base + EV_IN + goff[g]) : make_uint2(0u, 0u);
;     }
;   };
;     ...
;       float4 kk4 = *(const float4*)(sKk + sA_cc * 4);
;       float q0 = val[1][0] * kk4.x, q1 = val[1][1] * kk4.y, q2 = val[1][2] * kk4.z, q3 = val[1][3] * kk4.w;
;       float ss = red16(q0 * q0 + q1 * q1 + q2 * q2 + q3 * q3);
;       float rn = rsqrtf(ss + 1e-12f);
;       *(float4*)(sKK + so) = make_float4(q0 * rn, q1 * rn, q2 * rn, q3 * rn);
;       uint2 tw, ta;
;       tw.x = pack2(tanhf_(val[3][0]), tanhf_(val[3][1]));
;       tw.y = pack2(tanhf_(val[3][2]), tanhf_(val[3][3]));
;       ta.x = pack2(val[4][0], val[4][1]);
;       ta.y = pack2(val[4][2], val[4][3]);
;       *(uint2*)(sAw + sA_s * 72 + sA_cc * 4) = tw;
;       *(uint2*)(sAa + sA_s * 72 + sA_cc * 4) = ta;
;     }
;     lds_barrier();
;     if (gc + 1 < NGC) load_pre(gc + 1, pre, sA_s, sA_cc);
	v_lshlrev_b32_e32 v53, 16, v235
	v_lshlrev_b32_e32 v52, 16, v234
	v_lshlrev_b32_e32 v57, 16, v237
	v_lshlrev_b32_e32 v56, 16, v236
	s_waitcnt lgkmcnt(0)
	v_pk_mul_f32 v[18:19], v[18:19], v[22:23]
	v_pk_mul_f32 v[20:21], v[20:21], v[24:25]
	v_pk_mul_f32 v[22:23], v[18:19], v[18:19]
	v_pk_mul_f32 v[24:25], v[20:21], v[20:21]
	v_add_f32_e32 v22, v22, v23
	v_add_f32_e32 v22, v22, v24
	v_add_f32_e32 v22, v22, v25
	v_lshlrev_b32_e32 v61, 16, v239
	v_lshlrev_b32_e32 v60, 16, v238
	v_add_f32_dpp v22, v22, v22 quad_perm:[1,0,3,2] row_mask:0xf bank_mask:0xf bound_ctrl:1
	v_pk_add_f32 v[56:57], v[56:57], v[52:53] neg_lo:[0,1] neg_hi:[0,1]
	v_mov_b32_e32 v64, v30
	v_add_f32_dpp v22, v22, v22 quad_perm:[2,3,0,1] row_mask:0xf bank_mask:0xf bound_ctrl:1
	v_mov_b32_e32 v65, v32
	v_and_b32_e32 v55, 0xffff0000, v235
	v_add_f32_dpp v22, v22, v22 row_half_mirror row_mask:0xf bank_mask:0xf bound_ctrl:1
	v_and_b32_e32 v54, 0xffff0000, v234
	v_and_b32_e32 v59, 0xffff0000, v237
	v_add_f32_dpp v22, v22, v22 row_mirror row_mask:0xf bank_mask:0xf bound_ctrl:1
	v_add_f32_e32 v22, 0x2b8cbccc, v22
	v_cmp_gt_f32_e32 vcc, s62, v22
	v_mul_f32_e32 v23, 0x4b800000, v22
	v_and_b32_e32 v58, 0xffff0000, v236
	v_cndmask_b32_e32 v22, v22, v23, vcc
	v_rsq_f32_e32 v22, v22
	v_pk_fma_f32 v[56:57], v[56:57], v[64:65], v[52:53]
	v_pk_add_f32 v[52:53], v[60:61], v[52:53] neg_lo:[0,1] neg_hi:[0,1]
	v_mov_b32_e32 v60, v34
	v_mov_b32_e32 v61, v36
	v_mul_f32_e32 v23, 0x45800000, v22
	v_and_b32_e32 v63, 0xffff0000, v239
	v_and_b32_e32 v62, 0xffff0000, v238
	v_pk_fma_f32 v[52:53], v[52:53], v[60:61], v[56:57]
	v_pk_add_f32 v[56:57], v[58:59], v[54:55] neg_lo:[0,1] neg_hi:[0,1]
	v_mov_b32_e32 v32, v31
	v_cndmask_b32_e32 v22, v22, v23, vcc
	v_pk_fma_f32 v[30:31], v[56:57], v[32:33], v[54:55]
	v_pk_add_f32 v[32:33], v[62:63], v[54:55] neg_lo:[0,1] neg_hi:[0,1]
	v_mov_b32_e32 v36, v35
	v_pk_mul_f32 v[18:19], v[18:19], v[22:23] op_sel_hi:[1,0]
	v_pk_mul_f32 v[20:21], v[20:21], v[22:23] op_sel_hi:[1,0]
	v_pk_fma_f32 v[30:31], v[32:33], v[36:37], v[30:31]
	ds_write_b128 v50, v[18:21] offset:4096
	v_and_b32_sdwa v19, v52, v198 dst_sel:DWORD dst_unused:UNUSED_PAD src0_sel:WORD_1 src1_sel:DWORD
	v_add3_u32 v20, v52, v19, s63
	v_and_b32_sdwa v19, v31, v198 dst_sel:DWORD dst_unused:UNUSED_PAD src0_sel:WORD_1 src1_sel:DWORD
	v_and_b32_sdwa v21, v30, v198 dst_sel:DWORD dst_unused:UNUSED_PAD src0_sel:WORD_1 src1_sel:DWORD
	v_and_b32_sdwa v18, v53, v198 dst_sel:DWORD dst_unused:UNUSED_PAD src0_sel:WORD_1 src1_sel:DWORD
	v_add3_u32 v19, v31, v19, s63
	v_add3_u32 v21, v30, v21, s63
	v_add3_u32 v18, v53, v18, s63
	v_and_b32_e32 v19, 0xffff0000, v19
	v_and_b32_e32 v21, 0xffff0000, v21
	v_or_b32_sdwa v19, v19, v18 dst_sel:DWORD dst_unused:UNUSED_PAD src0_sel:DWORD src1_sel:WORD_1
	v_or_b32_sdwa v18, v21, v20 dst_sel:DWORD dst_unused:UNUSED_PAD src0_sel:DWORD src1_sel:WORD_1
	ds_write_b64 v51, v[46:47] offset:32768
	ds_write_b64 v51, v[18:19] offset:35072
	s_waitcnt lgkmcnt(0)
	s_barrier
	s_cmp_lt_u32 s27, 14
	s_movk_i32 s21, 0x1000
	s_cselect_b32 s22, 0x100, s21
	s_cselect_b32 s21, 32, 0xffffff20
	v_sub_u32_e32 v20, s22, v1
	v_subrev_u32_e32 v20, s21, v20
	v_add_u32_e32 v21, s21, v158
	v_add_u32_e32 v20, v167, v20
	v_add_u32_e32 v1, v21, v1
	s_cselect_b32 s20, s26, s25
	v_cndmask_b32_e64 v1, v20, v1, s[56:57]
	v_lshlrev_b32_e32 v18, 2, v48
	v_add_u32_e32 v22, s20, v1
	v_mov_b64_e32 v[20:21], s[18:19]
	v_ashrrev_i32_e32 v19, 31, v18
	v_mad_i64_i32 v[20:21], s[20:21], v22, s33, v[20:21]
	v_lshl_add_u64 v[20:21], v[18:19], 1, v[20:21]
	s_mov_b32 s59, s1
	s_mov_b32 s35, s1
	s_mov_b32 s61, s1
	s_mov_b32 s87, s1
	v_lshl_add_u64 v[18:19], v[20:21], 0, s[58:59]
	global_load_dwordx2 v[180:181], v[18:19], off
	v_lshl_add_u64 v[18:19], v[20:21], 0, s[0:1]
	global_load_dwordx2 v[186:187], v[18:19], off
	v_lshl_add_u64 v[18:19], v[20:21], 0, s[34:35]
	global_load_dwordx2 v[210:211], v[18:19], off
	v_lshl_add_u64 v[18:19], v[20:21], 0, s[60:61]
	global_load_dwordx2 v[216:217], v[18:19], off
	v_lshl_add_u64 v[18:19], v[20:21], 0, s[86:87]
	global_load_dwordx2 v[234:235], v[18:19], off
	v_mov_b32_e32 v182, v0
	v_mov_b32_e32 v183, v0
	v_mov_b32_e32 v184, v0
	v_mov_b32_e32 v185, v0
	v_mov_b32_e32 v188, v0
	v_mov_b32_e32 v189, v0
	v_mov_b32_e32 v190, v0
	v_mov_b32_e32 v191, v0
	v_mov_b32_e32 v212, v0
	v_mov_b32_e32 v213, v0
	v_mov_b32_e32 v214, v0
	v_mov_b32_e32 v215, v0
	v_mov_b32_e32 v218, v0
	v_mov_b32_e32 v219, v0
	v_mov_b32_e32 v220, v0
	v_mov_b32_e32 v221, v0
	v_mov_b32_e32 v236, v0
	v_mov_b32_e32 v237, v0
	v_mov_b32_e32 v238, v0
	v_mov_b32_e32 v239, v0
	v_cmp_lt_i32_e32 vcc, 0, v1
	s_add_i32 s22, s22, -1
	v_cmp_gt_i32_e64 s[42:43], s22, v1
	s_movk_i32 s20, 0xbe00
	s_mov_b32 s21, -1
	v_lshl_add_u64 v[22:23], v[20:21], 0, s[20:21]
	s_mov_b64 s[20:21], 0x4200
	v_lshl_add_u64 v[24:25], v[20:21], 0, s[20:21]
	s_mov_b64 s[20:21], exec
	s_and_b64 exec, s[20:21], vcc
	v_lshl_add_u64 v[18:19], v[22:23], 0, s[58:59]
	global_load_dwordx2 v[182:183], v[18:19], off
	v_lshl_add_u64 v[18:19], v[22:23], 0, s[0:1]
	global_load_dwordx2 v[188:189], v[18:19], off
	v_lshl_add_u64 v[18:19], v[22:23], 0, s[34:35]
	global_load_dwordx2 v[212:213], v[18:19], off
	v_lshl_add_u64 v[18:19], v[22:23], 0, s[60:61]
	global_load_dwordx2 v[218:219], v[18:19], off
	v_lshl_add_u64 v[18:19], v[22:23], 0, s[86:87]
	global_load_dwordx2 v[236:237], v[18:19], off
	s_and_b64 exec, s[20:21], s[42:43]
	v_lshl_add_u64 v[18:19], v[24:25], 0, s[58:59]
	global_load_dwordx2 v[184:185], v[18:19], off
	v_lshl_add_u64 v[18:19], v[24:25], 0, s[0:1]
	global_load_dwordx2 v[190:191], v[18:19], off
	v_lshl_add_u64 v[18:19], v[24:25], 0, s[34:35]
	global_load_dwordx2 v[214:215], v[18:19], off
	v_lshl_add_u64 v[18:19], v[24:25], 0, s[60:61]
	global_load_dwordx2 v[220:221], v[18:19], off
	v_lshl_add_u64 v[18:19], v[24:25], 0, s[86:87]
	global_load_dwordx2 v[238:239], v[18:19], off
	s_mov_b64 exec, s[20:21]
	s_branch .LBB0_474

; __device__ void natten_tile(int tid_, int bid_, int nblk_, const Params& p, int li, int wt) {
;     ...
;   const int y0 = min(max(y - 4, 0), 56);
;   const int c0 = (x0 == 0) ? 0 : (x0 == 16 ? 8 : (x0 == 32 ? 24 : 32));
;   const int xq = x0 + fr;
;   const int cs = min(max(xq - 8, 0), 48);
;   const float* rpb = p.ev_rpb + (size_t)(li * 16 + h) * 15 * 31;
;   bf16x8 bq[2];
;   {
;     const u16* qp = P + (qrow0 + fr) * EV_IN + 4352 + h * 64 + fq * 8;
;     bq[0] = *(const bf16x8*)(qp);
;     bq[1] = *(const bf16x8*)(qp + 32);
;   }
;   const int nblk = nloc + 8;
;   auto key_base = [&](int kb) -> size_t {
;     return (kb < nloc) ? ((size_t)b * SEQ + (y0 + kb) * 64 + c0) : ((size_t)MLAT + b * CTX + (kb - nloc) * 32);
;   };
;   auto scores = [&](int kb, f32x4& sa, f32x4& sb) {
;     size_t kr = key_base(kb);
;     const u16* kp = P + (kr + fr) * EV_IN + 5376 + h * 64 + fq * 8;
;     bf16x8 a0 = *(const bf16x8*)(kp);
;     bf16x8 a1 = *(const bf16x8*)(kp + 32);
;     bf16x8 a2 = *(const bf16x8*)(kp + (size_t)16 * EV_IN);
;     bf16x8 a3 = *(const bf16x8*)(kp + (size_t)16 * EV_IN + 32);
;     sa = f32x4{0.f, 0.f, 0.f, 0.f};
;     sb = f32x4{0.f, 0.f, 0.f, 0.f};
;     sa = __builtin_amdgcn_mfma_f32_16x16x32_bf16(a0, bq[0], sa, 0, 0, 0);
;     sa = __builtin_amdgcn_mfma_f32_16x16x32_bf16(a1, bq[1], sa, 0, 0, 0);
;     sb = __builtin_amdgcn_mfma_f32_16x16x32_bf16(a2, bq[0], sb, 0, 0, 0);
;     sb = __builtin_amdgcn_mfma_f32_16x16x32_bf16(a3, bq[1], sb, 0, 0, 0);
;     if (kb < nloc) {
;       const float* rb = rpb + (y0 + kb - y + 7) * 31;
; #pragma unroll
;       for (int j = 0; j < 4; ++j) {
;         int kc = c0 + fq * 4 + j;
;         int kc2 = kc + 16;
;         bool v1 = (kc >= cs) && (kc < cs + 16);
;         bool v2 = (kc2 >= cs) && (kc2 < cs + 16);
;         float b1 = v1 ? rb[kc - xq + 15] : 0.f;
;         float b2 = v2 ? rb[kc2 - xq + 15] : 0.f;
;         sa[j] = v1 ? sa[j] * 0.125f + b1 : -1e30f;
;         sb[j] = v2 ? sb[j] * 0.125f + b2 : -1e30f;
;       }
;     } else {
; #pragma unroll
;       for (int j = 0; j < 4; ++j) { sa[j] *= 0.125f; sb[j] *= 0.125f; }
;     }
;   };
;   const float THR = 0.f;
;   float mref = -1e30f;
;   f32x4 O[4];
; #pragma unroll
;   for (int nt = 0; nt < 4; ++nt) O[nt] = f32x4{0.f, 0.f, 0.f, 0.f};
.LBB0_526:
	v_and_b32_e32 v226, 12, v154
	v_lshlrev_b32_e32 v226, 1, v226
	v_and_b32_e32 v227, 3, v154
	v_or_b32_e32 v226, v226, v227
	v_mov_b32_e32 v227, 0
	s_or_b32 s42, s42, s21
	v_lshl_add_u64 v[2:3], s[42:43], 0, v[154:155]
	v_mov_b64_e32 v[4:5], s[18:19]
	v_mad_u64_u32 v[4:5], s[22:23], v2, s33, v[4:5]
	v_sub_u32_e64 v1, s26, 4 clamp
	v_mov_b32_e32 v2, v5
	s_and_b32 s24, s28, 15
	v_readfirstlane_b32 s0, v1
	v_mad_u64_u32 v[2:3], s[22:23], v3, s33, v[2:3]
	s_min_u32 s89, s0, 56
	v_mov_b32_e32 v5, v2
	s_lshl_b32 s0, s24, 7
	v_or_b32_e32 v1, s27, v154
	v_lshl_add_u64 v[2:3], v[4:5], 0, s[0:1]
	v_lshlrev_b32_e32 v162, 1, v156
	v_mov_b32_e32 v163, v0
	v_sub_u32_e64 v1, v1, 8 clamp
	v_lshl_add_u64 v[2:3], v[2:3], 0, v[162:163]
	v_add_co_u32_e32 v4, vcc, s2, v2
	v_min_u32_e32 v1, 48, v1
	v_add_u32_e32 v6, s29, v156
	v_addc_co_u32_e32 v5, vcc, 0, v3, vcc
	v_add_u32_e32 v7, 4, v6
	v_add_u32_e32 v8, 16, v1
	v_cmp_lt_u32_e32 vcc, v6, v1
	v_cmp_ge_u32_e64 s[44:45], v6, v8
	v_cmp_ge_u32_e64 s[46:47], v7, v1
	v_cmp_lt_u32_e64 s[98:99], v7, v8
	v_add_u32_e32 v7, 1, v6
	v_add_u32_e32 v9, 5, v6
	s_or_b64 s[44:45], vcc, s[44:45]
	s_and_b64 s[46:47], s[98:99], s[46:47]
	v_cmp_lt_u32_e32 vcc, v7, v1
	v_cmp_ge_u32_e64 s[48:49], v7, v8
	v_cmp_ge_u32_e64 s[50:51], v9, v1
	v_cmp_lt_u32_e64 s[98:99], v9, v8
	v_add_u32_e32 v7, 2, v6
	v_add_u32_e32 v9, 6, v6
	s_or_b64 s[48:49], vcc, s[48:49]
	s_and_b64 s[50:51], s[98:99], s[50:51]
	v_cmp_lt_u32_e32 vcc, v7, v1
	v_cmp_ge_u32_e64 s[52:53], v7, v8
	v_cmp_ge_u32_e64 s[54:55], v9, v1
	v_cmp_lt_u32_e64 s[98:99], v9, v8
	v_add_u32_e32 v7, 3, v6
	s_ashr_i32 s21, s20, 31
	s_or_b64 s[52:53], vcc, s[52:53]
	s_and_b64 s[54:55], s[98:99], s[54:55]
	v_add_u32_e32 v9, 7, v6
	v_cmp_lt_u32_e32 vcc, v7, v1
	v_cmp_ge_u32_e64 s[56:57], v7, v8
	s_lshl_b32 s22, s20, 8
	s_lshl_b64 s[40:41], s[20:21], 12
	s_or_b64 s[56:57], vcc, s[56:57]
	v_cmp_ge_u32_e64 s[58:59], v9, v1
	v_cmp_lt_u32_e64 s[98:99], v9, v8
	s_lshl_b32 s30, s95, 5
	s_lshl_b32 s87, s24, 6
	s_ashr_i32 s23, s22, 31
	s_or_b32 s40, s40, s29
	s_and_b64 s[58:59], s[98:99], s[58:59]
	s_xor_b64 s[36:37], s[44:45], -1
	v_lshl_or_b32 v1, s20, 10, v154
	s_lshl_b32 s0, s29, 1
	s_or_b32 s90, s95, 6
	s_sub_i32 s25, 0x4000, s30
	s_xor_b64 s[34:35], s[48:49], -1
	s_xor_b64 s[38:39], s[52:53], -1
	s_xor_b64 s[20:21], s[56:57], -1
	s_add_u32 s22, s22, s25
	s_addc_u32 s23, s23, 0
	s_sub_i32 s25, s89, s26
	s_mul_i32 s25, s25, 31
	s_add_i32 s28, s25, 31
	s_ashr_i32 s29, s28, 31
	v_lshlrev_b32_e32 v6, 2, v6
	v_mov_b32_e32 v7, v0
	s_mul_i32 s25, s26, 31
	s_mul_i32 s26, s89, 31
	v_lshl_add_u64 v[8:9], s[28:29], 2, v[6:7]
	v_add_lshl_u32 v10, v154, s27, 2
	s_sub_i32 s26, s26, s25
	v_sub_co_u32_e32 v12, vcc, v8, v10
	s_ashr_i32 s27, s26, 31
	s_nop 0
	v_subbrev_co_u32_e32 v13, vcc, 0, v9, vcc
	v_lshl_add_u64 v[6:7], s[26:27], 2, v[6:7]
	v_sub_co_u32_e32 v14, vcc, v6, v10
	s_mov_b64 s[26:27], 0x2200
	s_nop 0
	v_subbrev_co_u32_e32 v15, vcc, 0, v7, vcc
	v_lshl_add_u64 v[2:3], v[2:3], 0, s[26:27]
	global_load_dwordx4 v[4:7], v[4:5], off offset:512
	s_nop 0
	global_load_dwordx4 v[8:11], v[2:3], off offset:64
	v_or_b32_e32 v2, s87, v1
	v_ashrrev_i32_e32 v3, 31, v2
	v_lshlrev_b64 v[16:17], 9, v[2:3]
	v_lshlrev_b64 v[2:3], 13, v[2:3]
	v_lshl_add_u64 v[164:165], s[68:69], 0, v[16:17]
	v_lshl_add_u64 v[2:3], s[66:67], 0, v[2:3]
	v_readlane_b32 s64, v252, 33
	v_lshl_add_u64 v[166:167], v[2:3], 0, s[0:1]
	v_readlane_b32 s0, v254, 61
	v_readlane_b32 s70, v252, 39
	v_readlane_b32 s71, v252, 40
	v_mov_b32_e32 v2, v0
	v_mov_b32_e32 v3, v0
	s_mulk_i32 s24, 0x744
	s_mulk_i32 s0, 0x7440
	v_lshl_add_u64 v[168:169], s[70:71], 0, v[12:13]
	v_lshl_add_u64 v[170:171], s[70:71], 0, v[14:15]
	v_mov_b32_e32 v1, v0
	v_mov_b64_e32 v[26:27], v[2:3]
	v_mov_b64_e32 v[22:23], v[2:3]
	v_mov_b64_e32 v[18:19], v[2:3]
	v_mov_b64_e32 v[14:15], v[2:3]
	s_add_i32 s24, s0, s24
	s_mov_b32 s25, s1
	s_sub_i32 s93, 0, s30
	v_mov_b32_e32 v173, 0
	v_mov_b32_e32 v190, 0xf149f2ca
	v_mov_b64_e32 v[24:25], v[0:1]
	v_mov_b64_e32 v[20:21], v[0:1]
	v_mov_b64_e32 v[16:17], v[0:1]
	v_mov_b64_e32 v[12:13], v[0:1]
	s_mov_b32 s94, 0
	s_lshl_b32 s86, s89, 6
	v_readlane_b32 s65, v252, 34
	v_readlane_b32 s66, v252, 35
	v_readlane_b32 s67, v252, 36
	v_readlane_b32 s68, v252, 37
	v_readlane_b32 s69, v252, 38
	v_readlane_b32 s72, v252, 41
	v_readlane_b32 s73, v252, 42
	v_readlane_b32 s74, v252, 43
	v_readlane_b32 s75, v252, 44
	v_readlane_b32 s76, v252, 45
	v_readlane_b32 s77, v252, 46
	v_readlane_b32 s78, v252, 47
	v_readlane_b32 s79, v252, 48
; __device__ void natten_tile(int tid_, int bid_, int nblk_, const Params& p, int li, int wt) {
;     ...
;   auto scores = [&](int kb, f32x4& sa, f32x4& sb) {
;     size_t kr = key_base(kb);
;     const u16* kp = P + (kr + fr) * EV_IN + 5376 + h * 64 + fq * 8;
;     bf16x8 a0 = *(const bf16x8*)(kp);
;     bf16x8 a1 = *(const bf16x8*)(kp + 32);
;     bf16x8 a2 = *(const bf16x8*)(kp + (size_t)16 * EV_IN);
;     bf16x8 a3 = *(const bf16x8*)(kp + (size_t)16 * EV_IN + 32);
;     sa = f32x4{0.f, 0.f, 0.f, 0.f};
;     sb = f32x4{0.f, 0.f, 0.f, 0.f};
;     sa = __builtin_amdgcn_mfma_f32_16x16x32_bf16(a0, bq[0], sa, 0, 0, 0);
;     sa = __builtin_amdgcn_mfma_f32_16x16x32_bf16(a1, bq[1], sa, 0, 0, 0);
;     sb = __builtin_amdgcn_mfma_f32_16x16x32_bf16(a2, bq[0], sb, 0, 0, 0);
;     sb = __builtin_amdgcn_mfma_f32_16x16x32_bf16(a3, bq[1], sb, 0, 0, 0);
;     if (kb < nloc) {
;       const float* rb = rpb + (y0 + kb - y + 7) * 31;
; #pragma unroll
;       for (int j = 0; j < 4; ++j) {
;         int kc = c0 + fq * 4 + j;
;         int kc2 = kc + 16;
;         bool v1 = (kc >= cs) && (kc < cs + 16);
;         bool v2 = (kc2 >= cs) && (kc2 < cs + 16);
;         float b1 = v1 ? rb[kc - xq + 15] : 0.f;
;         float b2 = v2 ? rb[kc2 - xq + 15] : 0.f;
;         sa[j] = v1 ? sa[j] * 0.125f + b1 : -1e30f;
;         sb[j] = v2 ? sb[j] * 0.125f + b2 : -1e30f;
;       }
;     ...
;     const u16* vb;
;     size_t tstride;
;     if (kb < nloc) {
;       vb = p.vtL + ((size_t)(b * 1024 + h * 64 + fr)) * SEQ + (y0 + kb) * 64 + c0 + fq * 4;
;       tstride = SEQ;
;     } else {
;       vb = p.vtC + ((size_t)(b * 1024 + h * 64 + fr)) * CTX + (kb - nloc) * 32 + fq * 4;
;       tstride = CTX;
;     }
; #pragma unroll
;     for (int nt = 0; nt < 4; ++nt) {
;       const u16* vp = vb + (size_t)(nt * 16) * tstride;
;       uint2 lo = *(const uint2*)(vp);
;       uint2 hi = *(const uint2*)(vp + 16);
;       bf16x8 bv;
;       bv[0] = (short)(lo.x & 0xffff); bv[1] = (short)(lo.x >> 16); bv[2] = (short)(lo.y & 0xffff); bv[3] = (short)(lo.y >> 16);
;       bv[4] = (short)(hi.x & 0xffff); bv[5] = (short)(hi.x >> 16); bv[6] = (short)(hi.y & 0xffff); bv[7] = (short)(hi.y >> 16);
;       O[nt] = __builtin_amdgcn_mfma_f32_16x16x32_bf16(pa, bv, O[nt], 0, 0, 0);
;     }
.LBB0_527:
	s_cmp_lt_u32 s94, s95
	s_cselect_b64 s[60:61], -1, 0
	s_cmp_ge_u32 s94, s95
	s_cselect_b64 s[26:27], -1, 0
	s_and_b64 vcc, exec, s[26:27]
	s_mov_b64 s[28:29], s[22:23]
	s_cbranch_vccnz .LBB0_529
	s_add_i32 s0, s94, s89
	s_lshl_b32 s0, s0, 6
	s_add_u32 s28, s40, s0
	s_addc_u32 s29, s41, 0
	v_lshl_add_u64 v[216:217], v[170:171], 0, s[24:25]
	v_mov_b32_e32 v218, 0
	v_mov_b32_e32 v219, 0
	v_mov_b32_e32 v220, 0
	v_mov_b32_e32 v221, 0
	v_mov_b32_e32 v222, 0
	v_mov_b32_e32 v223, 0
	v_mov_b32_e32 v224, 0
	v_mov_b32_e32 v225, 0
	s_mov_b64 s[98:99], exec
	s_and_b64 exec, s[98:99], s[36:37]
	global_load_dword v218, v[216:217], off offset:928
	s_and_b64 exec, s[98:99], s[46:47]
	global_load_dword v219, v[216:217], off offset:944
	s_and_b64 exec, s[98:99], s[34:35]
	global_load_dword v220, v[216:217], off offset:932
	s_and_b64 exec, s[98:99], s[50:51]
	global_load_dword v221, v[216:217], off offset:948
	s_and_b64 exec, s[98:99], s[38:39]
	global_load_dword v222, v[216:217], off offset:936
	s_and_b64 exec, s[98:99], s[54:55]
	global_load_dword v223, v[216:217], off offset:952
	s_and_b64 exec, s[98:99], s[20:21]
	global_load_dword v224, v[216:217], off offset:940
	s_and_b64 exec, s[98:99], s[58:59]
	global_load_dword v225, v[216:217], off offset:956
	s_mov_b64 exec, s[98:99]
.LBB0_529:
	v_lshl_add_u64 v[2:3], s[28:29], 0, v[226:227]
	v_mov_b64_e32 v[28:29], s[18:19]
	v_mad_u64_u32 v[28:29], s[28:29], v2, s33, v[28:29]
	v_mov_b32_e32 v2, v29
	v_mad_u64_u32 v[2:3], s[28:29], v3, s33, v[2:3]
	v_mov_b32_e32 v29, v2
	s_lshl_b32 s0, s87, 1
	v_lshl_add_u64 v[2:3], v[28:29], 0, s[0:1]
	v_mov_b32_e32 v163, v0
	v_lshl_add_u64 v[2:3], v[2:3], 0, v[162:163]
	v_add_co_u32_e32 v28, vcc, s2, v2
	s_mov_b64 s[28:29], 0x2a00
	s_nop 0
	v_addc_co_u32_e32 v29, vcc, 0, v3, vcc
	global_load_dwordx4 v[28:31], v[28:29], off offset:2560
	v_add_co_u32_e32 v174, vcc, 0x12800, v2
	s_nop 1
	v_addc_co_u32_e32 v175, vcc, 0, v3, vcc
	v_lshl_add_u64 v[2:3], v[2:3], 0, s[28:29]
	global_load_dwordx4 v[36:39], v[2:3], off offset:64
	global_load_dwordx4 v[32:35], v[174:175], off offset:2560
	global_load_dwordx4 v[212:215], v[174:175], off offset:2624
	s_and_b64 s[98:99], s[60:61], exec
	v_cndmask_b32_e64 v211, v165, v167, s[60:61]
	v_cndmask_b32_e64 v210, v164, v166, s[60:61]
	s_cselect_b32 s98, s86, s93
	s_mov_b32 s99, 0
	v_lshl_add_u64 v[210:211], v[158:159], 2, v[210:211]
	v_lshl_add_u64 v[210:211], s[98:99], 1, v[210:211]
	s_mov_b32 s98, 0x20000
	s_cselect_b32 s98, s98, 0x2000
	global_load_dwordx4 v[236:239], v[210:211], off
	v_lshl_add_u64 v[210:211], v[210:211], 0, s[98:99]
	global_load_dwordx4 v[240:243], v[210:211], off
	v_lshl_add_u64 v[210:211], v[210:211], 0, s[98:99]
	global_load_dwordx4 v[244:247], v[210:211], off
	v_lshl_add_u64 v[210:211], v[210:211], 0, s[98:99]
	global_load_dwordx4 v[248:251], v[210:211], off
	s_andn2_b64 vcc, exec, s[26:27]
	s_mov_b64 s[26:27], -1
	s_waitcnt vmcnt(7)
	v_mfma_f32_16x16x32_bf16 v[28:31], v[28:31], v[4:7], 0
	s_waitcnt vmcnt(6)
	v_mfma_f32_16x16x32_bf16 v[36:39], v[36:39], v[8:11], v[28:31]
	s_nop 0
	s_nop 0
	s_waitcnt vmcnt(5)
	v_mfma_f32_16x16x32_bf16 v[32:35], v[32:35], v[4:7], 0
	s_waitcnt vmcnt(4)
	v_mfma_f32_16x16x32_bf16 v[32:35], v[212:215], v[8:11], v[32:35]
	s_cbranch_vccnz .LBB0_531
	s_mov_b32 s26, 0x3e000000
	s_nop 5
	v_pk_mul_f32 v[2:3], v[32:33], s[26:27] op_sel_hi:[1,0]
	v_mul_f32_e32 v163, 0x3e000000, v34
	v_pk_mul_f32 v[30:31], v[38:39], s[26:27] op_sel_hi:[1,0]
	v_pk_mul_f32 v[28:29], v[36:37], s[26:27] op_sel_hi:[1,0]
	v_mul_f32_e32 v178, 0x3e000000, v35
	s_mov_b64 s[26:27], 0

; __device__ void natten_tile(int tid_, int bid_, int nblk_, const Params& p, int li, int wt) {
;     ...
;   auto scores = [&](int kb, f32x4& sa, f32x4& sb) {
;     size_t kr = key_base(kb);
;     const u16* kp = P + (kr + fr) * EV_IN + 5376 + h * 64 + fq * 8;
;     bf16x8 a0 = *(const bf16x8*)(kp);
;     bf16x8 a1 = *(const bf16x8*)(kp + 32);
;     bf16x8 a2 = *(const bf16x8*)(kp + (size_t)16 * EV_IN);
;     bf16x8 a3 = *(const bf16x8*)(kp + (size_t)16 * EV_IN + 32);
;     sa = f32x4{0.f, 0.f, 0.f, 0.f};
;     sb = f32x4{0.f, 0.f, 0.f, 0.f};
;     sa = __builtin_amdgcn_mfma_f32_16x16x32_bf16(a0, bq[0], sa, 0, 0, 0);
;     sa = __builtin_amdgcn_mfma_f32_16x16x32_bf16(a1, bq[1], sa, 0, 0, 0);
;     sb = __builtin_amdgcn_mfma_f32_16x16x32_bf16(a2, bq[0], sb, 0, 0, 0);
;     sb = __builtin_amdgcn_mfma_f32_16x16x32_bf16(a3, bq[1], sb, 0, 0, 0);
;     if (kb < nloc) {
;       const float* rb = rpb + (y0 + kb - y + 7) * 31;
; #pragma unroll
;       for (int j = 0; j < 4; ++j) {
;         int kc = c0 + fq * 4 + j;
;         int kc2 = kc + 16;
;         bool v1 = (kc >= cs) && (kc < cs + 16);
;         bool v2 = (kc2 >= cs) && (kc2 < cs + 16);
;         float b1 = v1 ? rb[kc - xq + 15] : 0.f;
;     ...
;     float pv[8];
; #pragma unroll
;     for (int j = 0; j < 4; ++j) {
;       pv[j] = __expf(sa[j] - mref);
;       pv[4 + j] = __expf(sb[j] - mref);
;       lsum += pv[j] + pv[4 + j];
;     }
;     bf16x8 pa;
; #pragma unroll
;     for (int j = 0; j < 8; ++j) pa[j] = (short)f2bf(pv[j]);
;     const u16* vb;
;     size_t tstride;
;     if (kb < nloc) {
;       vb = p.vtL + ((size_t)(b * 1024 + h * 64 + fr)) * SEQ + (y0 + kb) * 64 + c0 + fq * 4;
;       tstride = SEQ;
;     } else {
;       vb = p.vtC + ((size_t)(b * 1024 + h * 64 + fr)) * CTX + (kb - nloc) * 32 + fq * 4;
;       tstride = CTX;
;     }
; #pragma unroll
;     for (int nt = 0; nt < 4; ++nt) {
;       const u16* vp = vb + (size_t)(nt * 16) * tstride;
;       uint2 lo = *(const uint2*)(vp);
;       uint2 hi = *(const uint2*)(vp + 16);
;       bf16x8 bv;
;       bv[0] = (short)(lo.x & 0xffff); bv[1] = (short)(lo.x >> 16); bv[2] = (short)(lo.y & 0xffff); bv[3] = (short)(lo.y >> 16);
;       bv[4] = (short)(hi.x & 0xffff); bv[5] = (short)(hi.x >> 16); bv[6] = (short)(hi.y & 0xffff); bv[7] = (short)(hi.y >> 16);
;       O[nt] = __builtin_amdgcn_mfma_f32_16x16x32_bf16(pa, bv, O[nt], 0, 0, 0);
;     }
.LBB0_551:
	v_sub_f32_e32 v2, v2, v190
	v_mul_f32_e32 v2, 0x3fb8aa3b, v2
	v_exp_f32_e32 v175, v2
	v_sub_f32_e32 v2, v29, v190
	v_mul_f32_e32 v2, 0x3fb8aa3b, v2
	v_exp_f32_e32 v172, v2
	v_sub_f32_e32 v2, v3, v190
	v_mul_f32_e32 v2, 0x3fb8aa3b, v2
	v_exp_f32_e32 v174, v2
	v_sub_f32_e32 v2, v30, v190
	v_mul_f32_e32 v2, 0x3fb8aa3b, v2
	v_exp_f32_e32 v177, v2
	v_sub_f32_e32 v2, v163, v190
	v_mul_f32_e32 v2, 0x3fb8aa3b, v2
	v_exp_f32_e32 v179, v2
	v_sub_f32_e32 v2, v31, v190
	v_mul_f32_e32 v2, 0x3fb8aa3b, v2
	v_exp_f32_e32 v176, v2
	v_sub_f32_e32 v2, v178, v190
	v_mul_f32_e32 v2, 0x3fb8aa3b, v2
	v_sub_f32_e32 v1, v28, v190
	v_exp_f32_e32 v178, v2
	v_mul_f32_e32 v1, 0x3fb8aa3b, v1
	v_exp_f32_e32 v1, v1
	v_bfe_u32 v3, v179, 16, 1
	v_bfe_u32 v2, v178, 16, 1
	v_bfe_u32 v28, v174, 16, 1
	v_bfe_u32 v29, v175, 16, 1
	v_bfe_u32 v30, v176, 16, 1
	v_bfe_u32 v31, v177, 16, 1
	v_add3_u32 v34, v177, v31, s63
	v_add3_u32 v35, v176, v30, s63
	v_add3_u32 v30, v175, v29, s63
	v_add3_u32 v38, v174, v28, s63
	v_add3_u32 v31, v179, v3, s63
	v_add3_u32 v39, v178, v2, s63
	s_and_b64 s[26:27], s[60:61], exec
	v_cndmask_b32_e64 v29, v165, v167, s[60:61]
	v_cndmask_b32_e64 v28, v164, v166, s[60:61]
	v_lshlrev_b32_e32 v2, 1, v158
	v_mov_b32_e32 v3, v0
	v_bfe_u32 v32, v172, 16, 1
	v_bfe_u32 v33, v1, 16, 1
	s_cselect_b32 s26, s86, s93
	v_lshl_add_u64 v[28:29], v[28:29], 0, v[2:3]
	s_mov_b32 s27, s1
	v_add3_u32 v33, v1, v33, s63
	v_add3_u32 v32, v172, v32, s63
	v_lshl_add_u64 v[36:37], s[26:27], 1, v[28:29]
	v_perm_b32 v29, v35, v34, s88
	v_perm_b32 v28, v32, v33, s88
	v_perm_b32 v31, v39, v31, s88
	v_perm_b32 v30, v38, v30, s88
	s_mov_b32 s26, 0x20000
	s_cselect_b32 s26, s26, 0x2000
	v_lshl_add_u64 v[38:39], v[36:37], 0, s[26:27]
	s_mov_b64 s[30:31], -1
	s_waitcnt vmcnt(3)
	s_nop 0
	s_nop 1
	v_mfma_f32_16x16x32_bf16 v[24:27], v[28:31], v[236:239], v[24:27]
	s_waitcnt vmcnt(2)
	s_nop 0
	s_nop 1
	v_mfma_f32_16x16x32_bf16 v[20:23], v[28:31], v[240:243], v[20:23]
	v_lshl_add_u64 v[34:35], v[38:39], 0, s[26:27]
	s_nop 0
	s_mov_b32 s26, 0x60000
	s_cselect_b32 s26, s26, 0x6000
	s_waitcnt vmcnt(1)
	s_nop 0
	s_nop 1
	v_mfma_f32_16x16x32_bf16 v[16:19], v[28:31], v[244:247], v[16:19]
	v_lshl_add_u64 v[34:35], v[36:37], 0, s[26:27]
	s_nop 0
	s_add_i32 s26, s94, 1
	s_cmp_lt_u32 s26, s95
	s_cselect_b64 s[60:61], -1, 0
	s_cmp_ge_u32 s26, s95
	s_cselect_b64 s[26:27], -1, 0
	s_and_b64 vcc, exec, s[60:61]
	s_waitcnt vmcnt(0)
	s_nop 0
	s_nop 1
	v_mfma_f32_16x16x32_bf16 v[12:15], v[28:31], v[248:251], v[12:15]
	s_cbranch_vccnz .LBB0_553
	s_add_u32 s28, s22, 32
	s_addc_u32 s29, s23, 0
	s_mov_b64 s[30:31], 0
.LBB0_553:
	s_andn2_b64 vcc, exec, s[30:31]
	s_cbranch_vccnz .LBB0_555
	s_add_i32 s28, s89, s94
	s_lshl_b32 s28, s28, 6
	s_add_i32 s28, s28, 64
	s_add_u32 s28, s40, s28
	s_addc_u32 s29, s41, 0
	v_lshl_add_u64 v[216:217], v[168:169], 0, s[24:25]
	v_mov_b32_e32 v218, 0
	v_mov_b32_e32 v219, 0
	v_mov_b32_e32 v220, 0
	v_mov_b32_e32 v221, 0
	v_mov_b32_e32 v222, 0
	v_mov_b32_e32 v223, 0
	v_mov_b32_e32 v224, 0
	v_mov_b32_e32 v225, 0
	s_mov_b64 s[98:99], exec
	s_and_b64 exec, s[98:99], s[36:37]
	global_load_dword v218, v[216:217], off offset:928
	s_and_b64 exec, s[98:99], s[46:47]
	global_load_dword v219, v[216:217], off offset:944
	s_and_b64 exec, s[98:99], s[34:35]
	global_load_dword v220, v[216:217], off offset:932
	s_and_b64 exec, s[98:99], s[50:51]
	global_load_dword v221, v[216:217], off offset:948
	s_and_b64 exec, s[98:99], s[38:39]
	global_load_dword v222, v[216:217], off offset:936
	s_and_b64 exec, s[98:99], s[54:55]
	global_load_dword v223, v[216:217], off offset:952
	s_and_b64 exec, s[98:99], s[20:21]
	global_load_dword v224, v[216:217], off offset:940
	s_and_b64 exec, s[98:99], s[58:59]
	global_load_dword v225, v[216:217], off offset:956
	s_mov_b64 exec, s[98:99]
.LBB0_555:
	v_lshl_add_u64 v[28:29], s[28:29], 0, v[226:227]
	v_mov_b64_e32 v[30:31], s[18:19]
	v_mad_u64_u32 v[30:31], s[28:29], v28, s33, v[30:31]
	v_mov_b32_e32 v28, v31
	v_mad_u64_u32 v[28:29], s[28:29], v29, s33, v[28:29]
	v_mov_b32_e32 v31, v28
	v_lshl_add_u64 v[28:29], v[30:31], 0, s[0:1]
	v_mov_b32_e32 v163, v0
	v_lshl_add_u64 v[36:37], v[28:29], 0, v[162:163]
	v_add_co_u32_e32 v28, vcc, s2, v36
	s_mov_b64 s[28:29], 0x2a00
	s_nop 0
	v_addc_co_u32_e32 v29, vcc, 0, v37, vcc
	global_load_dwordx4 v[28:31], v[28:29], off offset:2560
	v_add_co_u32_e32 v180, vcc, 0x12800, v36
	s_nop 1
	v_addc_co_u32_e32 v181, vcc, 0, v37, vcc
	v_lshl_add_u64 v[36:37], v[36:37], 0, s[28:29]
	global_load_dwordx4 v[36:39], v[36:37], off offset:64
	s_andn2_b64 vcc, exec, s[26:27]
	global_load_dwordx4 v[32:35], v[180:181], off offset:2560
	global_load_dwordx4 v[212:215], v[180:181], off offset:2624
	s_add_i32 s100, s93, 32
	s_add_i32 s101, s86, 64
	s_and_b64 s[98:99], s[60:61], exec
	v_cndmask_b32_e64 v211, v165, v167, s[60:61]
	v_cndmask_b32_e64 v210, v164, v166, s[60:61]
	s_cselect_b32 s98, s101, s100
	s_mov_b32 s99, 0
	v_lshl_add_u64 v[210:211], v[158:159], 2, v[210:211]
	v_lshl_add_u64 v[210:211], s[98:99], 1, v[210:211]
	s_mov_b32 s98, 0x20000
	s_cselect_b32 s98, s98, 0x2000
	global_load_dwordx4 v[236:239], v[210:211], off
	v_lshl_add_u64 v[210:211], v[210:211], 0, s[98:99]
	global_load_dwordx4 v[240:243], v[210:211], off
	v_lshl_add_u64 v[210:211], v[210:211], 0, s[98:99]
	global_load_dwordx4 v[244:247], v[210:211], off
	v_lshl_add_u64 v[210:211], v[210:211], 0, s[98:99]
	global_load_dwordx4 v[248:251], v[210:211], off
	s_mov_b64 s[26:27], -1
	s_waitcnt vmcnt(7)
	v_mfma_f32_16x16x32_bf16 v[28:31], v[28:31], v[4:7], 0
	s_waitcnt vmcnt(6)
	v_mfma_f32_16x16x32_bf16 v[36:39], v[36:39], v[8:11], v[28:31]
	s_nop 0
	s_nop 0
	s_waitcnt vmcnt(5)
	v_mfma_f32_16x16x32_bf16 v[32:35], v[32:35], v[4:7], 0
	s_waitcnt vmcnt(4)
	v_mfma_f32_16x16x32_bf16 v[32:35], v[212:215], v[8:11], v[32:35]
	s_cbranch_vccnz .LBB0_557
	s_mov_b32 s26, 0x3e000000
	s_nop 5
	v_pk_mul_f32 v[180:181], v[32:33], s[26:27] op_sel_hi:[1,0]
	v_mul_f32_e32 v3, 0x3e000000, v34
	v_pk_mul_f32 v[30:31], v[38:39], s[26:27] op_sel_hi:[1,0]
	v_pk_mul_f32 v[28:29], v[36:37], s[26:27] op_sel_hi:[1,0]
	v_mul_f32_e32 v163, 0x3e000000, v35
	s_mov_b64 s[26:27], 0

; __device__ void natten_tile(int tid_, int bid_, int nblk_, const Params& p, int li, int wt) {
;     ...
;     float pv[8];
; #pragma unroll
;     for (int j = 0; j < 4; ++j) {
;       pv[j] = __expf(sa[j] - mref);
;       pv[4 + j] = __expf(sb[j] - mref);
;       lsum += pv[j] + pv[4 + j];
;     }
;     bf16x8 pa;
; #pragma unroll
;     for (int j = 0; j < 8; ++j) pa[j] = (short)f2bf(pv[j]);
;     const u16* vb;
;     size_t tstride;
;     if (kb < nloc) {
;       vb = p.vtL + ((size_t)(b * 1024 + h * 64 + fr)) * SEQ + (y0 + kb) * 64 + c0 + fq * 4;
;       tstride = SEQ;
;     } else {
;       vb = p.vtC + ((size_t)(b * 1024 + h * 64 + fr)) * CTX + (kb - nloc) * 32 + fq * 4;
;       tstride = CTX;
;     }
; #pragma unroll
;     for (int nt = 0; nt < 4; ++nt) {
;       const u16* vp = vb + (size_t)(nt * 16) * tstride;
;       uint2 lo = *(const uint2*)(vp);
;       uint2 hi = *(const uint2*)(vp + 16);
;       bf16x8 bv;
;       bv[0] = (short)(lo.x & 0xffff); bv[1] = (short)(lo.x >> 16); bv[2] = (short)(lo.y & 0xffff); bv[3] = (short)(lo.y >> 16);
;       bv[4] = (short)(hi.x & 0xffff); bv[5] = (short)(hi.x >> 16); bv[6] = (short)(hi.y & 0xffff); bv[7] = (short)(hi.y >> 16);
;       O[nt] = __builtin_amdgcn_mfma_f32_16x16x32_bf16(pa, bv, O[nt], 0, 0, 0);
;     }
;   }
;   lsum += __shfl_xor(lsum, 16);
;   lsum += __shfl_xor(lsum, 32);
;   float inv = 1.f / lsum;
;   float invq[4];
; #pragma unroll
;   for (int j = 0; j < 4; ++j) invq[j] = __shfl(inv, fq * 4 + j);
.LBB0_577:
	v_sub_f32_e32 v1, v28, v190
	v_sub_f32_e32 v28, v180, v190
	v_mul_f32_e32 v28, 0x3fb8aa3b, v28
	v_exp_f32_e32 v36, v28
	v_sub_f32_e32 v28, v29, v190
	v_mul_f32_e32 v28, 0x3fb8aa3b, v28
	v_exp_f32_e32 v32, v28
	v_sub_f32_e32 v28, v181, v190
	v_mul_f32_e32 v28, 0x3fb8aa3b, v28
	v_mul_f32_e32 v1, 0x3fb8aa3b, v1
	v_exp_f32_e32 v34, v28
	v_sub_f32_e32 v28, v30, v190
	v_exp_f32_e32 v1, v1
	v_mul_f32_e32 v28, 0x3fb8aa3b, v28
	v_sub_f32_e32 v30, v163, v190
	v_exp_f32_e32 v37, v28
	v_sub_f32_e32 v3, v3, v190
	v_sub_f32_e32 v28, v31, v190
	v_mul_f32_e32 v30, 0x3fb8aa3b, v30
	v_mul_f32_e32 v3, 0x3fb8aa3b, v3
	v_mul_f32_e32 v28, 0x3fb8aa3b, v28
	v_exp_f32_e32 v30, v30
	v_exp_f32_e32 v3, v3
	v_exp_f32_e32 v28, v28
	v_add_f32_e32 v35, v1, v36
	v_bfe_u32 v174, v32, 16, 1
	v_add3_u32 v174, v32, v174, s63
	v_pk_add_f32 v[32:33], v[32:33], v[34:35]
	v_bfe_u32 v31, v30, 16, 1
	v_bfe_u32 v163, v36, 16, 1
	v_pk_add_f32 v[32:33], v[32:33], v[32:33] op_sel_hi:[0,1]
	v_add_f32_e32 v29, v37, v3
	v_bfe_u32 v172, v28, 16, 1
	v_add3_u32 v36, v36, v163, s63
	v_add3_u32 v163, v30, v31, s63
	v_mov_b32_e32 v31, v33
	v_bfe_u32 v38, v3, 16, 1
	v_bfe_u32 v173, v37, 16, 1
	v_add3_u32 v172, v28, v172, s63
	v_pk_add_f32 v[28:29], v[28:29], v[30:31]
	s_add_i32 s28, s93, 32
	s_add_i32 s29, s86, 64
	v_add3_u32 v37, v37, v173, s63
	v_add3_u32 v38, v3, v38, s63
	v_add_f32_e32 v173, v28, v29
	s_and_b64 s[26:27], exec, s[60:61]
	v_cndmask_b32_e64 v29, v165, v167, s[60:61]
	v_cndmask_b32_e64 v28, v164, v166, s[60:61]
	v_mov_b32_e32 v3, v0
	s_cselect_b32 s26, s29, s28
	v_lshl_add_u64 v[2:3], v[28:29], 0, v[2:3]
	s_mov_b32 s27, s1
	v_bfe_u32 v39, v34, 16, 1
	v_lshl_add_u64 v[2:3], s[26:27], 1, v[2:3]
	v_add3_u32 v39, v34, v39, s63
	v_bfe_u32 v175, v1, 16, 1
	v_add3_u32 v1, v1, v175, s63
	v_perm_b32 v31, v163, v38, s88
	v_perm_b32 v30, v39, v36, s88
	v_perm_b32 v29, v172, v37, s88
	v_perm_b32 v28, v174, v1, s88
	s_mov_b32 s26, 0x20000
	s_cselect_b32 s26, s26, 0x2000
	v_lshl_add_u64 v[36:37], v[2:3], 0, s[26:27]
	s_waitcnt vmcnt(3)
	s_nop 0
	s_nop 1
	v_mfma_f32_16x16x32_bf16 v[24:27], v[28:31], v[236:239], v[24:27]
	s_waitcnt vmcnt(2)
	s_nop 0
	s_nop 1
	v_mfma_f32_16x16x32_bf16 v[20:23], v[28:31], v[240:243], v[20:23]
	v_lshl_add_u64 v[34:35], v[36:37], 0, s[26:27]
	s_nop 0
	s_mov_b32 s26, 0x60000
	s_cselect_b32 s26, s26, 0x6000
	v_lshl_add_u64 v[2:3], v[2:3], 0, s[26:27]
	s_add_u32 s22, s22, 64
	s_mov_b64 s[26:27], 0xf8
	s_addc_u32 s23, s23, 0
	v_lshl_add_u64 v[168:169], v[168:169], 0, s[26:27]
	s_add_i32 s93, s93, 64
	s_addk_i32 s86, 0x80
	v_lshl_add_u64 v[170:171], v[170:171], 0, s[26:27]
	s_add_i32 s26, s94, 2
	s_cmp_lg_u32 s94, s90
	s_waitcnt vmcnt(1)
	s_nop 0
	s_nop 1
	v_mfma_f32_16x16x32_bf16 v[16:19], v[28:31], v[244:247], v[16:19]
	s_waitcnt vmcnt(0)
	s_nop 0
	s_nop 1
	v_mfma_f32_16x16x32_bf16 v[12:15], v[28:31], v[248:251], v[12:15]
	s_cbranch_scc0 .LBB0_579
	s_mov_b32 s94, s26
	s_branch .LBB0_527
.LBB0_579:
	v_mov_b32_e32 v222, 0x81
	v_mov_b32_e32 v223, 0x80
	v_mov_b32_e32 v224, 0x7f
	v_mov_b32_e32 v225, 0x1400
	v_mov_b32_e32 v226, 0x1e00
	v_mov_b32_e32 v227, 0xa00
	v_lshl_add_u64 v[4:5], s[42:43], 0, v[158:159]
	v_mov_b64_e32 v[2:3], s[18:19]
	v_mad_u64_u32 v[2:3], s[20:21], v4, s33, v[2:3]
	v_mov_b32_e32 v6, v3
	v_mad_u64_u32 v[6:7], s[20:21], v5, s33, v[6:7]
	v_mov_b32_e32 v3, v6
	v_lshlrev_b32_e32 v6, 1, v154
	v_mov_b32_e32 v7, v0
	v_lshl_add_u64 v[2:3], v[2:3], 0, s[0:1]
	v_lshl_add_u64 v[2:3], v[2:3], 0, v[6:7]
	s_mov_b64 s[98:99], 0x3a00
	v_lshl_add_u64 v[210:211], v[2:3], 0, s[98:99]
	s_mov_b64 s[98:99], 0x4200
	global_load_ushort v236, v[210:211], off
	global_load_ushort v237, v[210:211], off offset:32
	global_load_ushort v238, v[210:211], off offset:64
	global_load_ushort v239, v[210:211], off offset:96
	v_lshl_add_u64 v[210:211], v[210:211], 0, s[98:99]
	global_load_ushort v240, v[210:211], off
	global_load_ushort v241, v[210:211], off offset:32
	global_load_ushort v242, v[210:211], off offset:64
	global_load_ushort v243, v[210:211], off offset:96
	v_lshl_add_u64 v[210:211], v[210:211], 0, s[98:99]
	global_load_ushort v244, v[210:211], off
	global_load_ushort v245, v[210:211], off offset:32
	global_load_ushort v246, v[210:211], off offset:64
	global_load_ushort v247, v[210:211], off offset:96
	v_lshl_add_u64 v[210:211], v[210:211], 0, s[98:99]
	global_load_ushort v248, v[210:211], off
	global_load_ushort v249, v[210:211], off offset:32
	global_load_ushort v250, v[210:211], off offset:64
	global_load_ushort v251, v[210:211], off offset:96
	s_movk_i32 s20, 0x3000
	v_add_co_u32_e32 v8, vcc, s20, v2
	v_or_b32_e32 v10, v200, v158
	s_nop 0
	v_addc_co_u32_e32 v9, vcc, 0, v3, vcc
	v_cmp_lt_i32_e32 vcc, v203, v201
	v_lshlrev_b32_e32 v10, 2, v10
	v_readlane_b32 s36, v254, 11
	v_cndmask_b32_e32 v8, v199, v203, vcc
	v_lshlrev_b32_e32 v8, 2, v8
	ds_bpermute_b32 v8, v8, v173
	v_cmp_lt_i32_e32 vcc, v202, v201
	v_lshlrev_b64 v[4:5], 12, v[4:5]
	v_readlane_b32 s37, v254, 12
	v_cndmask_b32_e32 v9, v199, v202, vcc
	v_lshlrev_b32_e32 v9, 2, v9
	s_waitcnt lgkmcnt(0)
	v_add_f32_e32 v8, v173, v8
	ds_bpermute_b32 v9, v9, v8
	v_lshl_add_u64 v[4:5], s[36:37], 0, v[4:5]
	v_lshl_add_u64 v[4:5], v[4:5], 0, s[0:1]
	v_lshl_add_u64 v[4:5], v[4:5], 0, v[6:7]
	s_movk_i32 s0, 0x7000
	s_waitcnt lgkmcnt(0)
	v_add_f32_e32 v8, v8, v9
	v_div_scale_f32 v9, s[20:21], v8, v8, 1.0
	v_rcp_f32_e32 v11, v9
	v_div_scale_f32 v28, vcc, 1.0, v8, 1.0
	s_mov_b64 s[20:21], 0x3a00
	v_fma_f32 v29, -v9, v11, 1.0
	v_fmac_f32_e32 v11, v29, v11
	v_mul_f32_e32 v29, v28, v11
	v_fma_f32 v30, -v9, v29, v28
	v_fmac_f32_e32 v29, v30, v11
	v_fma_f32 v9, -v9, v29, v28
	v_div_fmas_f32 v9, v9, v11, v29
	v_div_fixup_f32 v11, v9, v8, 1.0
	ds_bpermute_b32 v8, v10, v11
	v_lshl_add_u64 v[6:7], v[2:3], 0, s[20:21]
	s_mov_b64 s[20:21], 0x1000
	v_readlane_b32 s34, v255, 8
	v_readlane_b32 s93, v254, 57
	s_waitcnt lgkmcnt(0)
; __device__ __forceinline__ float bf2f(u16 h) { return __uint_as_float(((unsigned)h) << 16); }
; __device__ __forceinline__ float siluf_(float x) { return x * __builtin_amdgcn_rcpf(1.f + __expf(-x)); }
; __device__ void natten_tile(int tid_, int bid_, int nblk_, const Params& p, int li, int wt) {
;     ...
; #pragma unroll
;   for (int j = 0; j < 4; ++j) {
;     size_t row = qrow0 + fq * 4 + j;
;     const u16* gp = P + row * EV_IN + 7424 + h * 64 + fr;
;     u16* yp = p.y + row * 2048 + 1024 + h * 64 + fr;
; #pragma unroll
;     for (int nt = 0; nt < 4; ++nt) {
;       float g = bf2f(gp[nt * 16]);
;       yp[nt * 16] = f2bf(O[nt][j] * invq[j] * siluf_(g));
;     }
;   }
	v_mul_f32_e32 v24, v24, v8
	v_mul_f32_e32 v20, v20, v8
	v_mul_f32_e32 v16, v16, v8
	v_mul_f32_e32 v8, v12, v8
	ds_bpermute_b32 v12, v10, v11 offset:4
	s_movk_i32 s89, 0x1400
	s_movk_i32 s90, 0x140
	v_readlane_b32 s60, v254, 63
	v_readlane_b32 s35, v255, 9
	s_waitcnt lgkmcnt(0)
	v_mul_f32_e32 v17, v17, v12
	v_readlane_b32 s30, v255, 4
	v_readlane_b32 s38, v254, 13
	v_readlane_b32 s39, v254, 14
	v_readlane_b32 s40, v254, 15
	v_readlane_b32 s41, v254, 16
	v_readlane_b32 s42, v254, 17
	v_readlane_b32 s43, v254, 18
	v_readlane_b32 s44, v254, 19
	v_readlane_b32 s45, v254, 20
	v_readlane_b32 s46, v254, 21
	v_readlane_b32 s47, v254, 22
	v_readlane_b32 s48, v254, 23
	v_readlane_b32 s49, v254, 24
	v_readlane_b32 s50, v254, 25
	v_readlane_b32 s51, v254, 26
	s_waitcnt vmcnt(0)
	v_mov_b32_e32 v1, v236
	v_lshlrev_b32_e32 v1, 16, v1
	v_mul_f32_e32 v28, 0xbfb8aa3b, v1
	v_exp_f32_e32 v28, v28
	s_nop 0
	v_add_f32_e32 v9, 1.0, v28
	v_rcp_f32_e32 v9, v9
	s_nop 0
	v_mul_f32_e32 v1, v9, v1
	v_mul_f32_e32 v1, v24, v1
	v_bfe_u32 v9, v1, 16, 1
	v_add3_u32 v1, v1, v9, s63
	global_store_short_d16_hi v[4:5], v1, off offset:2048
	v_mov_b32_e32 v1, v237
	v_lshlrev_b32_e32 v1, 16, v1
	v_mul_f32_e32 v9, 0xbfb8aa3b, v1
	v_exp_f32_e32 v9, v9
	s_nop 0
	v_add_f32_e32 v9, 1.0, v9
	v_rcp_f32_e32 v9, v9
	s_nop 0
	v_mul_f32_e32 v1, v9, v1
	v_mul_f32_e32 v1, v20, v1
	v_bfe_u32 v9, v1, 16, 1
	v_add3_u32 v1, v1, v9, s63
	global_store_short_d16_hi v[4:5], v1, off offset:2080
	v_mov_b32_e32 v1, v238
	v_mul_f32_e32 v20, v25, v12
	v_lshlrev_b32_e32 v1, 16, v1
	v_mul_f32_e32 v9, 0xbfb8aa3b, v1
	v_exp_f32_e32 v9, v9
	s_nop 0
	v_add_f32_e32 v9, 1.0, v9
	v_rcp_f32_e32 v9, v9
	s_nop 0
	v_mul_f32_e32 v1, v9, v1
	v_mul_f32_e32 v1, v16, v1
	v_bfe_u32 v9, v1, 16, 1
	v_add3_u32 v1, v1, v9, s63
	global_store_short_d16_hi v[4:5], v1, off offset:2112
	v_mov_b32_e32 v1, v239
	v_lshlrev_b32_e32 v1, 16, v1
	v_mul_f32_e32 v6, 0xbfb8aa3b, v1
	v_exp_f32_e32 v6, v6
	s_nop 0
	v_add_f32_e32 v6, 1.0, v6
	v_rcp_f32_e32 v9, v6
	v_add_co_u32_e32 v6, vcc, s0, v2
	s_mov_b32 s0, 0xb000
	v_mul_f32_e32 v1, v9, v1
	v_mul_f32_e32 v1, v8, v1
	v_bfe_u32 v8, v1, 16, 1
	v_add3_u32 v1, v1, v8, s63
	v_addc_co_u32_e32 v7, vcc, 0, v3, vcc
	global_store_short_d16_hi v[4:5], v1, off offset:2144
	v_mov_b32_e32 v1, v240
	v_lshlrev_b32_e32 v1, 16, v1
	v_mul_f32_e32 v6, 0xbfb8aa3b, v1
	v_exp_f32_e32 v6, v6
	s_nop 0
	v_add_f32_e32 v6, 1.0, v6
	v_rcp_f32_e32 v16, v6
	v_lshl_add_u64 v[6:7], v[4:5], 0, s[20:21]
	s_mov_b64 s[20:21], 0x7c00
	v_lshl_add_u64 v[8:9], v[2:3], 0, s[20:21]
	v_mul_f32_e32 v1, v16, v1
	v_mul_f32_e32 v1, v20, v1
	v_bfe_u32 v16, v1, 16, 1
	v_add3_u32 v1, v1, v16, s63
	global_store_short_d16_hi v[6:7], v1, off offset:2048
	v_mov_b32_e32 v1, v241
	v_mul_f32_e32 v20, v21, v12
	v_mul_f32_e32 v12, v13, v12
	s_mov_b64 s[20:21], 0x2000
	v_lshlrev_b32_e32 v1, 16, v1
	v_mul_f32_e32 v16, 0xbfb8aa3b, v1
	v_exp_f32_e32 v16, v16
	s_nop 0
	v_add_f32_e32 v16, 1.0, v16
	v_rcp_f32_e32 v16, v16
	s_nop 0
	v_mul_f32_e32 v1, v16, v1
	v_mul_f32_e32 v1, v20, v1
	v_bfe_u32 v16, v1, 16, 1
	v_add3_u32 v1, v1, v16, s63
	global_store_short_d16_hi v[6:7], v1, off offset:2080
	v_mov_b32_e32 v1, v242
	v_lshlrev_b32_e32 v1, 16, v1
	v_mul_f32_e32 v16, 0xbfb8aa3b, v1
	v_exp_f32_e32 v16, v16
	s_nop 0
	v_add_f32_e32 v16, 1.0, v16
	v_rcp_f32_e32 v16, v16
	s_nop 0
	v_mul_f32_e32 v1, v16, v1
	v_mul_f32_e32 v1, v17, v1
	v_bfe_u32 v16, v1, 16, 1
	v_add3_u32 v1, v1, v16, s63
	global_store_short_d16_hi v[6:7], v1, off offset:2112
	v_mov_b32_e32 v1, v243
	v_lshlrev_b32_e32 v1, 16, v1
	v_mul_f32_e32 v8, 0xbfb8aa3b, v1
	v_exp_f32_e32 v8, v8
	s_nop 0
	v_add_f32_e32 v8, 1.0, v8
	v_rcp_f32_e32 v16, v8
	v_add_co_u32_e32 v8, vcc, s0, v2
	s_mov_b32 s0, 0x10000
	v_mul_f32_e32 v1, v16, v1
	v_mul_f32_e32 v1, v12, v1
	v_bfe_u32 v12, v1, 16, 1
	v_add3_u32 v1, v1, v12, s63
	v_addc_co_u32_e32 v9, vcc, 0, v3, vcc
	global_store_short_d16_hi v[6:7], v1, off offset:2144
	v_mov_b32_e32 v1, v244
	ds_bpermute_b32 v12, v10, v11 offset:8
	s_waitcnt lgkmcnt(0)
; __device__ __forceinline__ float bf2f(u16 h) { return __uint_as_float(((unsigned)h) << 16); }
; __device__ __forceinline__ float siluf_(float x) { return x * __builtin_amdgcn_rcpf(1.f + __expf(-x)); }
; __device__ void natten_tile(int tid_, int bid_, int nblk_, const Params& p, int li, int wt) {
;     ...
; #pragma unroll
;   for (int j = 0; j < 4; ++j) {
;     size_t row = qrow0 + fq * 4 + j;
;     const u16* gp = P + row * EV_IN + 7424 + h * 64 + fr;
;     u16* yp = p.y + row * 2048 + 1024 + h * 64 + fr;
; #pragma unroll
;     for (int nt = 0; nt < 4; ++nt) {
;       float g = bf2f(gp[nt * 16]);
;       yp[nt * 16] = f2bf(O[nt][j] * invq[j] * siluf_(g));
;     }
;   }
	v_mul_f32_e32 v16, v26, v12
	v_lshlrev_b32_e32 v1, 16, v1
	v_mul_f32_e32 v6, 0xbfb8aa3b, v1
	v_exp_f32_e32 v6, v6
	s_nop 0
	v_add_f32_e32 v6, 1.0, v6
	v_rcp_f32_e32 v13, v6
	v_lshl_add_u64 v[6:7], v[4:5], 0, s[20:21]
	s_mov_b64 s[20:21], 0xbe00
	v_lshl_add_u64 v[8:9], v[2:3], 0, s[20:21]
	v_mul_f32_e32 v1, v13, v1
	v_mul_f32_e32 v1, v16, v1
	v_bfe_u32 v13, v1, 16, 1
	v_add3_u32 v1, v1, v13, s63
	global_store_short_d16_hi v[6:7], v1, off offset:2048
	v_mov_b32_e32 v1, v245
	v_mul_f32_e32 v16, v22, v12
	s_mov_b64 s[20:21], 0x3000
	v_lshl_add_u64 v[4:5], v[4:5], 0, s[20:21]
	s_mov_b64 s[20:21], 0x10000
	v_lshlrev_b32_e32 v1, 16, v1
	v_mul_f32_e32 v13, 0xbfb8aa3b, v1
	v_exp_f32_e32 v13, v13
	s_nop 0
	v_add_f32_e32 v13, 1.0, v13
	v_rcp_f32_e32 v13, v13
	s_nop 0
	v_mul_f32_e32 v1, v13, v1
	v_mul_f32_e32 v1, v16, v1
	v_bfe_u32 v13, v1, 16, 1
	v_add3_u32 v1, v1, v13, s63
	global_store_short_d16_hi v[6:7], v1, off offset:2080
	v_mov_b32_e32 v1, v246
	v_mul_f32_e32 v16, v18, v12
	v_mul_f32_e32 v12, v14, v12
	v_lshlrev_b32_e32 v1, 16, v1
	v_mul_f32_e32 v13, 0xbfb8aa3b, v1
	v_exp_f32_e32 v13, v13
	s_nop 0
	v_add_f32_e32 v13, 1.0, v13
	v_rcp_f32_e32 v13, v13
	s_nop 0
	v_mul_f32_e32 v1, v13, v1
	v_mul_f32_e32 v1, v16, v1
	v_bfe_u32 v13, v1, 16, 1
	v_add3_u32 v1, v1, v13, s63
	global_store_short_d16_hi v[6:7], v1, off offset:2112
	v_mov_b32_e32 v1, v247
	v_lshlrev_b32_e32 v1, 16, v1
	v_mul_f32_e32 v8, 0xbfb8aa3b, v1
	v_exp_f32_e32 v8, v8
	s_nop 0
	v_add_f32_e32 v8, 1.0, v8
	v_rcp_f32_e32 v13, v8
	v_add_co_u32_e32 v8, vcc, s0, v2
	v_mul_f32_e32 v1, v13, v1
	v_mul_f32_e32 v1, v12, v1
	v_bfe_u32 v12, v1, 16, 1
	v_add3_u32 v1, v1, v12, s63
	v_addc_co_u32_e32 v9, vcc, 0, v3, vcc
	global_store_short_d16_hi v[6:7], v1, off offset:2144
	v_mov_b32_e32 v1, v248
	v_or_b32_e32 v7, 12, v10
	ds_bpermute_b32 v7, v7, v11
	v_lshl_add_u64 v[2:3], v[2:3], 0, s[20:21]
	s_mov_b64 s[20:21], 0
	s_waitcnt lgkmcnt(0)
	v_mul_f32_e32 v8, v27, v7
	v_lshlrev_b32_e32 v1, 16, v1
	v_mul_f32_e32 v6, 0xbfb8aa3b, v1
	v_exp_f32_e32 v6, v6
	s_nop 0
	v_add_f32_e32 v6, 1.0, v6
	v_rcp_f32_e32 v6, v6
	s_nop 0
	v_mul_f32_e32 v1, v6, v1
	v_mul_f32_e32 v1, v8, v1
	v_bfe_u32 v6, v1, 16, 1
	v_add3_u32 v1, v1, v6, s63
	global_store_short_d16_hi v[4:5], v1, off offset:2048
	v_mov_b32_e32 v1, v249
	v_mul_f32_e32 v8, v23, v7
	v_lshlrev_b32_e32 v1, 16, v1
	v_mul_f32_e32 v6, 0xbfb8aa3b, v1
	v_exp_f32_e32 v6, v6
	s_nop 0
	v_add_f32_e32 v6, 1.0, v6
	v_rcp_f32_e32 v6, v6
	s_nop 0
	v_mul_f32_e32 v1, v6, v1
	v_mul_f32_e32 v1, v8, v1
	v_bfe_u32 v6, v1, 16, 1
	v_add3_u32 v1, v1, v6, s63
	global_store_short_d16_hi v[4:5], v1, off offset:2080
	v_mov_b32_e32 v1, v250
	v_mul_f32_e32 v8, v19, v7
	v_lshlrev_b32_e32 v1, 16, v1
	v_mul_f32_e32 v6, 0xbfb8aa3b, v1
	v_exp_f32_e32 v6, v6
	s_nop 0
	v_add_f32_e32 v6, 1.0, v6
	v_rcp_f32_e32 v6, v6
	s_nop 0
	v_mul_f32_e32 v1, v6, v1
	v_mul_f32_e32 v1, v8, v1
	v_bfe_u32 v6, v1, 16, 1
	v_add3_u32 v1, v1, v6, s63
	global_store_short_d16_hi v[4:5], v1, off offset:2112
	v_mov_b32_e32 v1, v251
	v_mul_f32_e32 v3, v15, v7
	v_lshlrev_b32_e32 v1, 16, v1
	v_mul_f32_e32 v2, 0xbfb8aa3b, v1
	v_exp_f32_e32 v2, v2
	s_nop 0
	v_add_f32_e32 v2, 1.0, v2
	v_rcp_f32_e32 v2, v2
	s_nop 0
	v_mul_f32_e32 v1, v2, v1
	v_mul_f32_e32 v1, v3, v1
	v_bfe_u32 v2, v1, 16, 1
	v_add3_u32 v1, v1, v2, s63
	global_store_short_d16_hi v[4:5], v1, off offset:2144
